# v9 + attention cross-half row max via v_permlane32_swap instead of ds_bpermute + lgkmcnt wait (22 sites)
# speedup vs baseline: 1.0120x; 1.0120x over previous
.LBB0_608:
	s_waitcnt vmcnt(3)
	v_mfma_f32_32x32x16_bf16 v[34:49], v[78:81], v[50:53], 0
	v_lshl_add_u64 v[110:111], s[18:19], 0, v[98:99]
	s_waitcnt vmcnt(2)
	v_mfma_f32_32x32x16_bf16 v[34:49], v[74:77], v[54:57], v[34:49]
	v_lshl_add_u64 v[74:75], s[14:15], 0, v[98:99]
	v_add_co_u32_e32 v74, vcc, 0xe500000, v74
	s_nop 1
	v_addc_co_u32_e32 v75, vcc, 0, v75, vcc
	global_load_dwordx4 v[94:97], v[74:75], off
	global_load_dwordx4 v[90:93], v[74:75], off offset:1024
	global_load_dwordx4 v[82:85], v[74:75], off offset:2048
	global_load_dwordx4 v[86:89], v[74:75], off offset:3072
	s_waitcnt vmcnt(5)
	v_mfma_f32_32x32x16_bf16 v[34:49], v[70:73], v[58:61], v[34:49]
	global_load_dwordx4 v[78:81], v[110:111], off offset:-2048
	global_load_dwordx4 v[74:77], v[110:111], off offset:-1024
	s_waitcnt vmcnt(6)
	v_mfma_f32_32x32x16_bf16 v[34:49], v[66:69], v[62:65], v[34:49]
	global_load_dwordx4 v[70:73], v[110:111], off
	global_load_dwordx4 v[66:69], v[110:111], off offset:1024
	s_nop 9
	v_max_f32_e32 v0, v35, v35
	v_max_f32_e32 v105, v34, v34
	v_max_f32_e32 v0, v105, v0
	v_max_f32_e32 v105, v37, v37
	v_max_f32_e32 v106, v36, v36
	v_max_f32_e32 v105, v106, v105
	v_max_f32_e32 v106, v41, v41
	v_max_f32_e32 v110, v40, v40
	v_max_f32_e32 v106, v110, v106
	v_max3_f32 v106, v38, v39, v106
	v_max3_f32 v0, v0, v105, v106
	v_max_f32_e32 v105, v45, v45
	v_max_f32_e32 v106, v44, v44
	v_max_f32_e32 v105, v106, v105
	v_max_f32_e32 v106, v49, v49
	v_max_f32_e32 v110, v48, v48
	v_max_f32_e32 v106, v110, v106
	v_max3_f32 v105, v42, v43, v105
	v_max3_f32 v106, v46, v47, v106
	v_max3_f32 v0, v0, v105, v106
	v_mov_b32_e32 v105, v0
	s_nop 1
	v_permlane32_swap_b32_e32 v0, v105
	s_waitcnt lgkmcnt(0)
	v_max_f32_e32 v105, v105, v105
	v_max_f32_e32 v0, v0, v105
	v_cmp_gt_f32_e32 vcc, v0, v115
	s_cbranch_vccz .LBB0_607
	v_max_f32_e32 v0, v0, v0
	v_max_f32_e32 v105, v115, v115
	v_max_f32_e32 v105, v105, v0
	v_sub_f32_e32 v0, v115, v105
	v_exp_f32_e32 v0, v0
	v_mov_b32_e32 v115, v105
	v_mul_f32_e32 v108, v108, v0
	v_pk_mul_f32 v[32:33], v[32:33], v[0:1] op_sel_hi:[1,0]
	v_pk_mul_f32 v[30:31], v[30:31], v[0:1] op_sel_hi:[1,0]
	v_pk_mul_f32 v[28:29], v[28:29], v[0:1] op_sel_hi:[1,0]
	v_pk_mul_f32 v[26:27], v[26:27], v[0:1] op_sel_hi:[1,0]
	v_pk_mul_f32 v[24:25], v[24:25], v[0:1] op_sel_hi:[1,0]
	v_pk_mul_f32 v[22:23], v[22:23], v[0:1] op_sel_hi:[1,0]
	v_pk_mul_f32 v[20:21], v[20:21], v[0:1] op_sel_hi:[1,0]
	v_pk_mul_f32 v[18:19], v[18:19], v[0:1] op_sel_hi:[1,0]
	v_pk_mul_f32 v[16:17], v[16:17], v[0:1] op_sel_hi:[1,0]
	v_pk_mul_f32 v[14:15], v[14:15], v[0:1] op_sel_hi:[1,0]
	v_pk_mul_f32 v[12:13], v[12:13], v[0:1] op_sel_hi:[1,0]
	v_pk_mul_f32 v[10:11], v[10:11], v[0:1] op_sel_hi:[1,0]
	v_pk_mul_f32 v[8:9], v[8:9], v[0:1] op_sel_hi:[1,0]
	v_pk_mul_f32 v[6:7], v[6:7], v[0:1] op_sel_hi:[1,0]
	v_pk_mul_f32 v[4:5], v[4:5], v[0:1] op_sel_hi:[1,0]
	v_pk_mul_f32 v[2:3], v[2:3], v[0:1] op_sel_hi:[1,0]
	s_branch .LBB0_607
.LBB0_610:
	s_waitcnt vmcnt(3)
	v_mfma_f32_32x32x16_bf16 v[34:49], v[78:81], v[50:53], 0
	s_add_u32 s14, s10, s30
	s_addc_u32 s15, s11, s29
	v_mov_b32_e32 v105, v1
	v_lshl_add_u64 v[78:79], s[14:15], 0, v[104:105]
	s_waitcnt vmcnt(2)
	v_mfma_f32_32x32x16_bf16 v[34:49], v[74:77], v[54:57], v[34:49]
	v_add_co_u32_e32 v74, vcc, 0x7000, v78
	s_nop 1
	v_addc_co_u32_e32 v75, vcc, 0, v79, vcc
	global_load_dwordx4 v[82:85], v[74:75], off
	global_load_dwordx4 v[78:81], v[74:75], off offset:1024
	s_waitcnt vmcnt(3)
	v_mfma_f32_32x32x16_bf16 v[34:49], v[70:73], v[58:61], v[34:49]
	global_load_dwordx4 v[70:73], v[74:75], off offset:2048
	s_nop 0
	global_load_dwordx4 v[74:77], v[74:75], off offset:3072
	s_waitcnt vmcnt(4)
	v_mfma_f32_32x32x16_bf16 v[34:49], v[66:69], v[62:65], v[34:49]
	s_nop 11
	v_max_f32_e32 v0, v35, v35
	v_max_f32_e32 v66, v34, v34
	v_max_f32_e32 v0, v66, v0
	v_max_f32_e32 v66, v37, v37
	v_max_f32_e32 v67, v36, v36
	v_max_f32_e32 v66, v67, v66
	v_max_f32_e32 v67, v41, v41
	v_max_f32_e32 v68, v40, v40
	v_max_f32_e32 v67, v68, v67
	v_max3_f32 v67, v38, v39, v67
	v_max3_f32 v0, v0, v66, v67
	v_max_f32_e32 v66, v45, v45
	v_max_f32_e32 v67, v44, v44
	v_max_f32_e32 v66, v67, v66
	v_max_f32_e32 v67, v49, v49
	v_max_f32_e32 v68, v48, v48
	v_max_f32_e32 v67, v68, v67
	v_max3_f32 v66, v42, v43, v66
	v_max3_f32 v67, v46, v47, v67
	v_max3_f32 v0, v0, v66, v67
	v_mov_b32_e32 v66, v0
	s_nop 1
	v_permlane32_swap_b32_e32 v0, v66
	s_waitcnt lgkmcnt(0)
	v_max_f32_e32 v66, v66, v66
	v_max_f32_e32 v0, v0, v66
	v_cmp_gt_f32_e32 vcc, v0, v115
	s_cbranch_vccz .LBB0_612
	v_max_f32_e32 v0, v0, v0
	v_max_f32_e32 v66, v115, v115
	v_max_f32_e32 v66, v66, v0
	v_sub_f32_e32 v0, v115, v66
	v_exp_f32_e32 v0, v0
	v_mov_b32_e32 v115, v66
	v_mul_f32_e32 v108, v108, v0
	v_pk_mul_f32 v[32:33], v[32:33], v[0:1] op_sel_hi:[1,0]
	v_pk_mul_f32 v[30:31], v[30:31], v[0:1] op_sel_hi:[1,0]
	v_pk_mul_f32 v[28:29], v[28:29], v[0:1] op_sel_hi:[1,0]
	v_pk_mul_f32 v[26:27], v[26:27], v[0:1] op_sel_hi:[1,0]
	v_pk_mul_f32 v[24:25], v[24:25], v[0:1] op_sel_hi:[1,0]
	v_pk_mul_f32 v[22:23], v[22:23], v[0:1] op_sel_hi:[1,0]
	v_pk_mul_f32 v[20:21], v[20:21], v[0:1] op_sel_hi:[1,0]
	v_pk_mul_f32 v[18:19], v[18:19], v[0:1] op_sel_hi:[1,0]
	v_pk_mul_f32 v[16:17], v[16:17], v[0:1] op_sel_hi:[1,0]
	v_pk_mul_f32 v[14:15], v[14:15], v[0:1] op_sel_hi:[1,0]
	v_pk_mul_f32 v[12:13], v[12:13], v[0:1] op_sel_hi:[1,0]
	v_pk_mul_f32 v[10:11], v[10:11], v[0:1] op_sel_hi:[1,0]
	v_pk_mul_f32 v[8:9], v[8:9], v[0:1] op_sel_hi:[1,0]
	v_pk_mul_f32 v[6:7], v[6:7], v[0:1] op_sel_hi:[1,0]
	v_pk_mul_f32 v[4:5], v[4:5], v[0:1] op_sel_hi:[1,0]
	v_pk_mul_f32 v[2:3], v[2:3], v[0:1] op_sel_hi:[1,0]

.LBB0_619:
	v_cmp_lt_u32_e32 vcc, s83, v105
	s_nop 9
	v_cndmask_b32_e32 v116, v237, v34, vcc
	v_add_u32_e32 v34, 1, v105
	v_cmp_lt_u32_e32 vcc, s83, v34
	v_add_u32_e32 v34, 2, v105
	s_nop 0
	v_cndmask_b32_e32 v117, v237, v35, vcc
	v_cmp_lt_u32_e32 vcc, s83, v34
	v_add_u32_e32 v34, 3, v105
	s_nop 0
	v_cndmask_b32_e32 v118, v237, v36, vcc
	v_cmp_lt_u32_e32 vcc, s83, v34
	v_add_u32_e32 v34, 8, v105
	s_nop 0
	v_cndmask_b32_e32 v35, v237, v37, vcc
	v_cmp_lt_u32_e32 vcc, s83, v34
	v_add_u32_e32 v34, 9, v105
	s_nop 0
	v_cndmask_b32_e32 v36, v237, v38, vcc
	v_cmp_lt_u32_e32 vcc, s83, v34
	v_add_u32_e32 v34, 10, v105
	s_nop 0
	v_cndmask_b32_e32 v37, v237, v39, vcc
	v_cmp_lt_u32_e32 vcc, s83, v34
	v_add_u32_e32 v34, 11, v105
	s_nop 0
	v_cndmask_b32_e32 v38, v237, v40, vcc
	v_cmp_lt_u32_e32 vcc, s83, v34
	v_add_u32_e32 v34, 16, v105
	v_max_f32_e32 v119, v38, v38
	v_cndmask_b32_e32 v39, v237, v41, vcc
	v_cmp_lt_u32_e32 vcc, s83, v34
	v_add_u32_e32 v34, 17, v105
	s_nop 0
	v_cndmask_b32_e32 v40, v237, v42, vcc
	v_cmp_lt_u32_e32 vcc, s83, v34
	v_add_u32_e32 v34, 18, v105
	s_nop 0
	v_cndmask_b32_e32 v41, v237, v43, vcc
	v_cmp_lt_u32_e32 vcc, s83, v34
	v_add_u32_e32 v34, 19, v105
	s_nop 0
	v_cndmask_b32_e32 v42, v237, v44, vcc
	v_cmp_lt_u32_e32 vcc, s83, v34
	v_add_u32_e32 v34, 24, v105
	s_nop 0
	v_cndmask_b32_e32 v43, v237, v45, vcc
	v_cmp_lt_u32_e32 vcc, s83, v34
	v_add_u32_e32 v34, 25, v105
	s_nop 0
	v_cndmask_b32_e32 v44, v237, v46, vcc
	v_cmp_lt_u32_e32 vcc, s83, v34
	v_add_u32_e32 v34, 26, v105
	s_nop 0
	v_cndmask_b32_e32 v45, v237, v47, vcc
	v_cmp_lt_u32_e32 vcc, s83, v34
	v_add_u32_e32 v34, 27, v105
	v_max_f32_e32 v47, v116, v116
	v_cndmask_b32_e32 v46, v237, v48, vcc
	v_cmp_lt_u32_e32 vcc, s83, v34
	v_max_f32_e32 v48, v117, v117
	v_max_f32_e32 v47, v47, v48
	v_cndmask_b32_e32 v34, v237, v49, vcc
	v_max_f32_e32 v48, v35, v35
	v_max_f32_e32 v49, v118, v118
	v_max_f32_e32 v48, v49, v48
	v_max_f32_e32 v49, v39, v39
	v_max_f32_e32 v49, v119, v49
	v_max3_f32 v49, v36, v37, v49
	v_max3_f32 v47, v47, v48, v49
	v_max_f32_e32 v48, v43, v43
	v_max_f32_e32 v49, v42, v42
	v_max_f32_e32 v48, v49, v48
	v_max_f32_e32 v49, v34, v34
	v_max_f32_e32 v119, v46, v46
	v_max_f32_e32 v49, v119, v49
	v_max3_f32 v48, v40, v41, v48
	v_max3_f32 v49, v44, v45, v49
	v_max3_f32 v47, v47, v48, v49
	v_mov_b32_e32 v48, v47
	s_nop 1
	v_permlane32_swap_b32_e32 v47, v48
	s_waitcnt lgkmcnt(0)
	v_max_f32_e32 v48, v48, v48
	v_max_f32_e32 v47, v47, v48
	v_cmp_gt_f32_e32 vcc, v47, v115
	s_cbranch_vccz .LBB0_616
	v_max_f32_e32 v47, v47, v47
	v_max_f32_e32 v48, v115, v115
	v_max_f32_e32 v47, v48, v47
	v_sub_f32_e32 v48, v115, v47
	v_exp_f32_e32 v48, v48
	v_mov_b32_e32 v115, v47
	v_mul_f32_e32 v0, v0, v48
	v_pk_mul_f32 v[32:33], v[32:33], v[48:49] op_sel_hi:[1,0]
	v_pk_mul_f32 v[30:31], v[30:31], v[48:49] op_sel_hi:[1,0]
	v_pk_mul_f32 v[28:29], v[28:29], v[48:49] op_sel_hi:[1,0]
	v_pk_mul_f32 v[26:27], v[26:27], v[48:49] op_sel_hi:[1,0]
	v_pk_mul_f32 v[24:25], v[24:25], v[48:49] op_sel_hi:[1,0]
	v_pk_mul_f32 v[22:23], v[22:23], v[48:49] op_sel_hi:[1,0]
	v_pk_mul_f32 v[20:21], v[20:21], v[48:49] op_sel_hi:[1,0]
	v_pk_mul_f32 v[18:19], v[18:19], v[48:49] op_sel_hi:[1,0]
	v_pk_mul_f32 v[16:17], v[16:17], v[48:49] op_sel_hi:[1,0]
	v_pk_mul_f32 v[14:15], v[14:15], v[48:49] op_sel_hi:[1,0]
	v_pk_mul_f32 v[12:13], v[12:13], v[48:49] op_sel_hi:[1,0]
	v_pk_mul_f32 v[10:11], v[10:11], v[48:49] op_sel_hi:[1,0]
	v_pk_mul_f32 v[8:9], v[8:9], v[48:49] op_sel_hi:[1,0]
	v_pk_mul_f32 v[6:7], v[6:7], v[48:49] op_sel_hi:[1,0]
	v_pk_mul_f32 v[4:5], v[4:5], v[48:49] op_sel_hi:[1,0]
	v_pk_mul_f32 v[2:3], v[2:3], v[48:49] op_sel_hi:[1,0]
	s_branch .LBB0_616

.LBB0_627:
	s_waitcnt vmcnt(3)
	v_mfma_f32_32x32x16_bf16 v[34:49], v[78:81], v[62:65], 0
	v_lshl_add_u64 v[110:111], s[14:15], 0, v[98:99]
	s_waitcnt vmcnt(2)
	v_mfma_f32_32x32x16_bf16 v[34:49], v[74:77], v[58:61], v[34:49]
	v_lshl_add_u64 v[74:75], s[6:7], 0, v[98:99]
	v_add_co_u32_e32 v74, vcc, 0xc500000, v74
	s_nop 1
	v_addc_co_u32_e32 v75, vcc, 0, v75, vcc
	global_load_dwordx4 v[94:97], v[74:75], off
	global_load_dwordx4 v[90:93], v[74:75], off offset:1024
	global_load_dwordx4 v[82:85], v[74:75], off offset:2048
	global_load_dwordx4 v[86:89], v[74:75], off offset:3072
	s_waitcnt vmcnt(5)
	v_mfma_f32_32x32x16_bf16 v[34:49], v[70:73], v[54:57], v[34:49]
	global_load_dwordx4 v[78:81], v[110:111], off offset:-2048
	global_load_dwordx4 v[74:77], v[110:111], off offset:-1024
	s_waitcnt vmcnt(6)
	v_mfma_f32_32x32x16_bf16 v[34:49], v[66:69], v[50:53], v[34:49]
	global_load_dwordx4 v[70:73], v[110:111], off
	global_load_dwordx4 v[66:69], v[110:111], off offset:1024
	s_nop 9
	v_max_f32_e32 v0, v35, v35
	v_max_f32_e32 v110, v34, v34
	v_max_f32_e32 v0, v110, v0
	v_max_f32_e32 v110, v37, v37
	v_max_f32_e32 v111, v36, v36
	v_max_f32_e32 v110, v111, v110
	v_max_f32_e32 v111, v41, v41
	v_max_f32_e32 v112, v40, v40
	v_max_f32_e32 v111, v112, v111
	v_max3_f32 v111, v38, v39, v111
	v_max3_f32 v0, v0, v110, v111
	v_max_f32_e32 v110, v45, v45
	v_max_f32_e32 v111, v44, v44
	v_max_f32_e32 v110, v111, v110
	v_max_f32_e32 v111, v49, v49
	v_max_f32_e32 v112, v48, v48
	v_max_f32_e32 v111, v112, v111
	v_max3_f32 v110, v42, v43, v110
	v_max3_f32 v111, v46, v47, v111
	v_max3_f32 v0, v0, v110, v111
	v_mov_b32_e32 v110, v0
	s_nop 1
	v_permlane32_swap_b32_e32 v0, v110
	s_waitcnt lgkmcnt(0)
	v_max_f32_e32 v110, v110, v110
	v_max_f32_e32 v0, v0, v110
	v_cmp_gt_f32_e32 vcc, v0, v107
	s_cbranch_vccz .LBB0_626
	v_max_f32_e32 v0, v0, v0
	v_max_f32_e32 v110, v107, v107
	v_max_f32_e32 v110, v110, v0
	v_sub_f32_e32 v0, v107, v110
	v_exp_f32_e32 v0, v0
	v_mov_b32_e32 v107, v110
	v_mul_f32_e32 v109, v109, v0
	v_pk_mul_f32 v[32:33], v[32:33], v[0:1] op_sel_hi:[1,0]
	v_pk_mul_f32 v[30:31], v[30:31], v[0:1] op_sel_hi:[1,0]
	v_pk_mul_f32 v[28:29], v[28:29], v[0:1] op_sel_hi:[1,0]
	v_pk_mul_f32 v[26:27], v[26:27], v[0:1] op_sel_hi:[1,0]
	v_pk_mul_f32 v[24:25], v[24:25], v[0:1] op_sel_hi:[1,0]
	v_pk_mul_f32 v[22:23], v[22:23], v[0:1] op_sel_hi:[1,0]
	v_pk_mul_f32 v[20:21], v[20:21], v[0:1] op_sel_hi:[1,0]
	v_pk_mul_f32 v[18:19], v[18:19], v[0:1] op_sel_hi:[1,0]
	v_pk_mul_f32 v[16:17], v[16:17], v[0:1] op_sel_hi:[1,0]
	v_pk_mul_f32 v[14:15], v[14:15], v[0:1] op_sel_hi:[1,0]
	v_pk_mul_f32 v[12:13], v[12:13], v[0:1] op_sel_hi:[1,0]
	v_pk_mul_f32 v[10:11], v[10:11], v[0:1] op_sel_hi:[1,0]
	v_pk_mul_f32 v[8:9], v[8:9], v[0:1] op_sel_hi:[1,0]
	v_pk_mul_f32 v[6:7], v[6:7], v[0:1] op_sel_hi:[1,0]
	v_pk_mul_f32 v[4:5], v[4:5], v[0:1] op_sel_hi:[1,0]
	v_pk_mul_f32 v[2:3], v[2:3], v[0:1] op_sel_hi:[1,0]
	s_branch .LBB0_626
.LBB0_629:
	s_waitcnt vmcnt(3)
	v_mfma_f32_32x32x16_bf16 v[34:49], v[78:81], v[62:65], 0
	s_or_b32 s6, s19, s23
	s_ashr_i32 s7, s6, 31
	s_lshl_b64 s[6:7], s[6:7], 9
	v_lshl_add_u64 v[62:63], v[100:101], 0, s[6:7]
	s_waitcnt vmcnt(2)
	v_mfma_f32_32x32x16_bf16 v[34:49], v[74:77], v[58:61], v[34:49]
	v_add_co_u32_e32 v74, vcc, 0x7000, v62
	s_nop 1
	v_addc_co_u32_e32 v75, vcc, 0, v63, vcc
	global_load_dwordx4 v[58:61], v[74:75], off
	global_load_dwordx4 v[62:65], v[74:75], off offset:1024
	s_waitcnt vmcnt(3)
	v_mfma_f32_32x32x16_bf16 v[34:49], v[70:73], v[54:57], v[34:49]
	global_load_dwordx4 v[54:57], v[74:75], off offset:2048
	global_load_dwordx4 v[70:73], v[74:75], off offset:3072
	s_waitcnt vmcnt(4)
	v_mfma_f32_32x32x16_bf16 v[34:49], v[66:69], v[50:53], v[34:49]
	s_nop 11
	v_max_f32_e32 v0, v35, v35
	v_max_f32_e32 v50, v34, v34
	v_max_f32_e32 v0, v50, v0
	v_max_f32_e32 v50, v37, v37
	v_max_f32_e32 v51, v36, v36
	v_max_f32_e32 v50, v51, v50
	v_max_f32_e32 v51, v41, v41
	v_max_f32_e32 v52, v40, v40
	v_max_f32_e32 v51, v52, v51
	v_max3_f32 v51, v38, v39, v51
	v_max3_f32 v0, v0, v50, v51
	v_max_f32_e32 v50, v45, v45
	v_max_f32_e32 v51, v44, v44
	v_max_f32_e32 v50, v51, v50
	v_max_f32_e32 v51, v49, v49
	v_max_f32_e32 v52, v48, v48
	v_max_f32_e32 v51, v52, v51
	v_max3_f32 v50, v42, v43, v50
	v_max3_f32 v51, v46, v47, v51
	v_max3_f32 v0, v0, v50, v51
	v_mov_b32_e32 v50, v0
	s_nop 1
	v_permlane32_swap_b32_e32 v0, v50
	s_waitcnt lgkmcnt(0)
	v_max_f32_e32 v50, v50, v50
	v_max_f32_e32 v0, v0, v50
	v_cmp_gt_f32_e32 vcc, v0, v107
	s_cbranch_vccz .LBB0_624
	v_max_f32_e32 v0, v0, v0
	v_max_f32_e32 v50, v107, v107
	v_max_f32_e32 v50, v50, v0
	v_sub_f32_e32 v0, v107, v50
	v_exp_f32_e32 v0, v0
	v_mov_b32_e32 v107, v50
	v_mul_f32_e32 v109, v109, v0
	v_pk_mul_f32 v[32:33], v[32:33], v[0:1] op_sel_hi:[1,0]
	v_pk_mul_f32 v[30:31], v[30:31], v[0:1] op_sel_hi:[1,0]
	v_pk_mul_f32 v[28:29], v[28:29], v[0:1] op_sel_hi:[1,0]
	v_pk_mul_f32 v[26:27], v[26:27], v[0:1] op_sel_hi:[1,0]
	v_pk_mul_f32 v[24:25], v[24:25], v[0:1] op_sel_hi:[1,0]
	v_pk_mul_f32 v[22:23], v[22:23], v[0:1] op_sel_hi:[1,0]
	v_pk_mul_f32 v[20:21], v[20:21], v[0:1] op_sel_hi:[1,0]
	v_pk_mul_f32 v[18:19], v[18:19], v[0:1] op_sel_hi:[1,0]
	v_pk_mul_f32 v[16:17], v[16:17], v[0:1] op_sel_hi:[1,0]
	v_pk_mul_f32 v[14:15], v[14:15], v[0:1] op_sel_hi:[1,0]
	v_pk_mul_f32 v[12:13], v[12:13], v[0:1] op_sel_hi:[1,0]
	v_pk_mul_f32 v[10:11], v[10:11], v[0:1] op_sel_hi:[1,0]
	v_pk_mul_f32 v[8:9], v[8:9], v[0:1] op_sel_hi:[1,0]
	v_pk_mul_f32 v[6:7], v[6:7], v[0:1] op_sel_hi:[1,0]
	v_pk_mul_f32 v[4:5], v[4:5], v[0:1] op_sel_hi:[1,0]
	v_pk_mul_f32 v[2:3], v[2:3], v[0:1] op_sel_hi:[1,0]
	s_branch .LBB0_624

.LBB0_635:
	s_waitcnt vmcnt(1)
	v_mfma_f32_32x32x16_bf16 v[34:49], v[78:81], v[50:53], 0
	v_lshl_add_u64 v[104:105], s[24:25], 0, v[98:99]
	v_mfma_f32_32x32x16_bf16 v[34:49], v[74:77], v[54:57], v[34:49]
	v_lshl_add_u64 v[74:75], s[6:7], 0, v[98:99]
	v_add_co_u32_e32 v74, vcc, 0xe500000, v74
	s_nop 1
	v_addc_co_u32_e32 v75, vcc, 0, v75, vcc
	global_load_dwordx4 v[94:97], v[74:75], off
	global_load_dwordx4 v[90:93], v[74:75], off offset:1024
	global_load_dwordx4 v[82:85], v[74:75], off offset:2048
	global_load_dwordx4 v[86:89], v[74:75], off offset:3072
	v_mfma_f32_32x32x16_bf16 v[34:49], v[70:73], v[58:61], v[34:49]
	global_load_dwordx4 v[78:81], v[104:105], off offset:-2048
	global_load_dwordx4 v[74:77], v[104:105], off offset:-1024
	s_waitcnt vmcnt(6)
	v_mfma_f32_32x32x16_bf16 v[34:49], v[66:69], v[62:65], v[34:49]
	global_load_dwordx4 v[70:73], v[104:105], off
	global_load_dwordx4 v[66:69], v[104:105], off offset:1024
	s_nop 9
	v_max_f32_e32 v0, v35, v35
	v_max_f32_e32 v104, v34, v34
	v_max_f32_e32 v0, v104, v0
	v_max_f32_e32 v104, v37, v37
	v_max_f32_e32 v105, v36, v36
	v_max_f32_e32 v104, v105, v104
	v_max_f32_e32 v105, v41, v41
	v_max_f32_e32 v107, v40, v40
	v_max_f32_e32 v105, v107, v105
	v_max3_f32 v105, v38, v39, v105
	v_max3_f32 v0, v0, v104, v105
	v_max_f32_e32 v104, v45, v45
	v_max_f32_e32 v105, v44, v44
	v_max_f32_e32 v104, v105, v104
	v_max_f32_e32 v105, v49, v49
	v_max_f32_e32 v107, v48, v48
	v_max_f32_e32 v105, v107, v105
	v_max3_f32 v104, v42, v43, v104
	v_max3_f32 v105, v46, v47, v105
	v_max3_f32 v0, v0, v104, v105
	v_mov_b32_e32 v104, v0
	s_nop 1
	v_permlane32_swap_b32_e32 v0, v104
	s_waitcnt lgkmcnt(0)
	v_max_f32_e32 v104, v104, v104
	v_max_f32_e32 v0, v0, v104
	v_cmp_gt_f32_e32 vcc, v0, v106
	s_cbranch_vccz .LBB0_634
	v_max_f32_e32 v0, v0, v0
	v_max_f32_e32 v104, v106, v106
	v_max_f32_e32 v104, v104, v0
	v_sub_f32_e32 v0, v106, v104
	v_exp_f32_e32 v0, v0
	v_mov_b32_e32 v106, v104
	v_mul_f32_e32 v102, v102, v0
	v_pk_mul_f32 v[32:33], v[32:33], v[0:1] op_sel_hi:[1,0]
	v_pk_mul_f32 v[30:31], v[30:31], v[0:1] op_sel_hi:[1,0]
	v_pk_mul_f32 v[28:29], v[28:29], v[0:1] op_sel_hi:[1,0]
	v_pk_mul_f32 v[26:27], v[26:27], v[0:1] op_sel_hi:[1,0]
	v_pk_mul_f32 v[24:25], v[24:25], v[0:1] op_sel_hi:[1,0]
	v_pk_mul_f32 v[22:23], v[22:23], v[0:1] op_sel_hi:[1,0]
	v_pk_mul_f32 v[20:21], v[20:21], v[0:1] op_sel_hi:[1,0]
	v_pk_mul_f32 v[18:19], v[18:19], v[0:1] op_sel_hi:[1,0]
	v_pk_mul_f32 v[16:17], v[16:17], v[0:1] op_sel_hi:[1,0]
	v_pk_mul_f32 v[14:15], v[14:15], v[0:1] op_sel_hi:[1,0]
	v_pk_mul_f32 v[12:13], v[12:13], v[0:1] op_sel_hi:[1,0]
	v_pk_mul_f32 v[10:11], v[10:11], v[0:1] op_sel_hi:[1,0]
	v_pk_mul_f32 v[8:9], v[8:9], v[0:1] op_sel_hi:[1,0]
	v_pk_mul_f32 v[6:7], v[6:7], v[0:1] op_sel_hi:[1,0]
	v_pk_mul_f32 v[4:5], v[4:5], v[0:1] op_sel_hi:[1,0]
	v_pk_mul_f32 v[2:3], v[2:3], v[0:1] op_sel_hi:[1,0]
	s_branch .LBB0_634
.LBB0_637:
	s_waitcnt vmcnt(3)
	v_mfma_f32_32x32x16_bf16 v[34:49], v[78:81], v[50:53], 0
	s_load_dwordx4 s[24:27], s[48:49], 0x140
	v_lshlrev_b32_e32 v0, 1, v100
	s_waitcnt lgkmcnt(0)
	s_add_u32 s6, s26, s11
	s_addc_u32 s7, s27, s10
	s_waitcnt vmcnt(2)
	v_mfma_f32_32x32x16_bf16 v[34:49], v[74:77], v[54:57], v[34:49]
	v_lshl_add_u64 v[78:79], s[6:7], 0, v[0:1]
	v_add_co_u32_e32 v86, vcc, 0xe507000, v78
	s_nop 1
	v_addc_co_u32_e32 v87, vcc, 0, v79, vcc
	global_load_dwordx4 v[82:85], v[86:87], off
	global_load_dwordx4 v[78:81], v[86:87], off offset:1024
	s_waitcnt vmcnt(3)
	v_mfma_f32_32x32x16_bf16 v[34:49], v[70:73], v[58:61], v[34:49]
	global_load_dwordx4 v[74:77], v[86:87], off offset:2048
	global_load_dwordx4 v[70:73], v[86:87], off offset:3072
	s_waitcnt vmcnt(4)
	v_mfma_f32_32x32x16_bf16 v[34:49], v[66:69], v[62:65], v[34:49]
	s_nop 11
	v_max_f32_e32 v66, v35, v35
	v_max_f32_e32 v67, v34, v34
	v_max_f32_e32 v66, v67, v66
	v_max_f32_e32 v67, v37, v37
	v_max_f32_e32 v68, v36, v36
	v_max_f32_e32 v67, v68, v67
	v_max_f32_e32 v68, v41, v41
	v_max_f32_e32 v69, v40, v40
	v_max_f32_e32 v68, v69, v68
	v_max3_f32 v68, v38, v39, v68
	v_max3_f32 v66, v66, v67, v68
	v_max_f32_e32 v67, v45, v45
	v_max_f32_e32 v68, v44, v44
	v_max_f32_e32 v67, v68, v67
	v_max_f32_e32 v68, v49, v49
	v_max_f32_e32 v69, v48, v48
	v_max_f32_e32 v68, v69, v68
	v_max3_f32 v67, v42, v43, v67
	v_max3_f32 v68, v46, v47, v68
	v_max3_f32 v66, v66, v67, v68
	v_mov_b32_e32 v67, v66
	s_nop 1
	v_permlane32_swap_b32_e32 v66, v67
	s_waitcnt lgkmcnt(0)
	v_max_f32_e32 v67, v67, v67
	v_max_f32_e32 v66, v66, v67
	v_cmp_gt_f32_e32 vcc, v66, v106
	s_cbranch_vccz .LBB0_639
	v_max_f32_e32 v66, v66, v66
	v_max_f32_e32 v67, v106, v106
	v_max_f32_e32 v67, v67, v66
	v_sub_f32_e32 v66, v106, v67
	v_exp_f32_e32 v66, v66
	v_mov_b32_e32 v106, v67
	v_mul_f32_e32 v102, v102, v66
	v_pk_mul_f32 v[32:33], v[32:33], v[66:67] op_sel_hi:[1,0]
	v_pk_mul_f32 v[30:31], v[30:31], v[66:67] op_sel_hi:[1,0]
	v_pk_mul_f32 v[28:29], v[28:29], v[66:67] op_sel_hi:[1,0]
	v_pk_mul_f32 v[26:27], v[26:27], v[66:67] op_sel_hi:[1,0]
	v_pk_mul_f32 v[24:25], v[24:25], v[66:67] op_sel_hi:[1,0]
	v_pk_mul_f32 v[22:23], v[22:23], v[66:67] op_sel_hi:[1,0]
	v_pk_mul_f32 v[20:21], v[20:21], v[66:67] op_sel_hi:[1,0]
	v_pk_mul_f32 v[18:19], v[18:19], v[66:67] op_sel_hi:[1,0]
	v_pk_mul_f32 v[16:17], v[16:17], v[66:67] op_sel_hi:[1,0]
	v_pk_mul_f32 v[14:15], v[14:15], v[66:67] op_sel_hi:[1,0]
	v_pk_mul_f32 v[12:13], v[12:13], v[66:67] op_sel_hi:[1,0]
	v_pk_mul_f32 v[10:11], v[10:11], v[66:67] op_sel_hi:[1,0]
	v_pk_mul_f32 v[8:9], v[8:9], v[66:67] op_sel_hi:[1,0]
	v_pk_mul_f32 v[6:7], v[6:7], v[66:67] op_sel_hi:[1,0]
	v_pk_mul_f32 v[4:5], v[4:5], v[66:67] op_sel_hi:[1,0]
	v_pk_mul_f32 v[2:3], v[2:3], v[66:67] op_sel_hi:[1,0]

.LBB0_646:
	v_cmp_lt_u32_e32 vcc, s83, v108
	s_nop 9
	v_cndmask_b32_e32 v109, v237, v34, vcc
	v_add_u32_e32 v34, 1, v108
	v_cmp_lt_u32_e32 vcc, s83, v34
	v_add_u32_e32 v34, 2, v108
	s_nop 0
	v_cndmask_b32_e32 v113, v237, v35, vcc
	v_cmp_lt_u32_e32 vcc, s83, v34
	v_add_u32_e32 v34, 3, v108
	s_nop 0
	v_cndmask_b32_e32 v114, v237, v36, vcc
	v_cmp_lt_u32_e32 vcc, s83, v34
	v_add_u32_e32 v34, 8, v108
	s_nop 0
	v_cndmask_b32_e32 v35, v237, v37, vcc
	v_cmp_lt_u32_e32 vcc, s83, v34
	v_add_u32_e32 v34, 9, v108
	s_nop 0
	v_cndmask_b32_e32 v36, v237, v38, vcc
	v_cmp_lt_u32_e32 vcc, s83, v34
	v_add_u32_e32 v34, 10, v108
	s_nop 0
	v_cndmask_b32_e32 v37, v237, v39, vcc
	v_cmp_lt_u32_e32 vcc, s83, v34
	v_add_u32_e32 v34, 11, v108
	s_nop 0
	v_cndmask_b32_e32 v38, v237, v40, vcc
	v_cmp_lt_u32_e32 vcc, s83, v34
	v_add_u32_e32 v34, 16, v108
	v_max_f32_e32 v115, v38, v38
	v_cndmask_b32_e32 v39, v237, v41, vcc
	v_cmp_lt_u32_e32 vcc, s83, v34
	v_add_u32_e32 v34, 17, v108
	s_nop 0
	v_cndmask_b32_e32 v40, v237, v42, vcc
	v_cmp_lt_u32_e32 vcc, s83, v34
	v_add_u32_e32 v34, 18, v108
	s_nop 0
	v_cndmask_b32_e32 v41, v237, v43, vcc
	v_cmp_lt_u32_e32 vcc, s83, v34
	v_add_u32_e32 v34, 19, v108
	s_nop 0
	v_cndmask_b32_e32 v42, v237, v44, vcc
	v_cmp_lt_u32_e32 vcc, s83, v34
	v_add_u32_e32 v34, 24, v108
	s_nop 0
	v_cndmask_b32_e32 v43, v237, v45, vcc
	v_cmp_lt_u32_e32 vcc, s83, v34
	v_add_u32_e32 v34, 25, v108
	s_nop 0
	v_cndmask_b32_e32 v44, v237, v46, vcc
	v_cmp_lt_u32_e32 vcc, s83, v34
	v_add_u32_e32 v34, 26, v108
	s_nop 0
	v_cndmask_b32_e32 v45, v237, v47, vcc
	v_cmp_lt_u32_e32 vcc, s83, v34
	v_add_u32_e32 v34, 27, v108
	v_max_f32_e32 v47, v109, v109
	v_cndmask_b32_e32 v46, v237, v48, vcc
	v_cmp_lt_u32_e32 vcc, s83, v34
	v_max_f32_e32 v48, v113, v113
	v_max_f32_e32 v47, v47, v48
	v_cndmask_b32_e32 v34, v237, v49, vcc
	v_max_f32_e32 v48, v35, v35
	v_max_f32_e32 v49, v114, v114
	v_max_f32_e32 v48, v49, v48
	v_max_f32_e32 v49, v39, v39
	v_max_f32_e32 v49, v115, v49
	v_max3_f32 v49, v36, v37, v49
	v_max3_f32 v47, v47, v48, v49
	v_max_f32_e32 v48, v43, v43
	v_max_f32_e32 v49, v42, v42
	v_max_f32_e32 v48, v49, v48
	v_max_f32_e32 v49, v34, v34
	v_max_f32_e32 v115, v46, v46
	v_max_f32_e32 v49, v115, v49
	v_max3_f32 v48, v40, v41, v48
	v_max3_f32 v49, v44, v45, v49
	v_max3_f32 v47, v47, v48, v49
	v_mov_b32_e32 v48, v47
	s_nop 1
	v_permlane32_swap_b32_e32 v47, v48
	s_waitcnt lgkmcnt(0)
	v_max_f32_e32 v48, v48, v48
	v_max_f32_e32 v47, v47, v48
	v_cmp_gt_f32_e32 vcc, v47, v106
	s_cbranch_vccz .LBB0_643
	v_max_f32_e32 v47, v47, v47
	v_max_f32_e32 v48, v106, v106
	v_max_f32_e32 v47, v48, v47
	v_sub_f32_e32 v48, v106, v47
	v_exp_f32_e32 v48, v48
	v_mov_b32_e32 v106, v47
	v_mul_f32_e32 v107, v107, v48
	v_pk_mul_f32 v[32:33], v[32:33], v[48:49] op_sel_hi:[1,0]
	v_pk_mul_f32 v[30:31], v[30:31], v[48:49] op_sel_hi:[1,0]
	v_pk_mul_f32 v[28:29], v[28:29], v[48:49] op_sel_hi:[1,0]
	v_pk_mul_f32 v[26:27], v[26:27], v[48:49] op_sel_hi:[1,0]
	v_pk_mul_f32 v[24:25], v[24:25], v[48:49] op_sel_hi:[1,0]
	v_pk_mul_f32 v[22:23], v[22:23], v[48:49] op_sel_hi:[1,0]
	v_pk_mul_f32 v[20:21], v[20:21], v[48:49] op_sel_hi:[1,0]
	v_pk_mul_f32 v[18:19], v[18:19], v[48:49] op_sel_hi:[1,0]
	v_pk_mul_f32 v[16:17], v[16:17], v[48:49] op_sel_hi:[1,0]
	v_pk_mul_f32 v[14:15], v[14:15], v[48:49] op_sel_hi:[1,0]
	v_pk_mul_f32 v[12:13], v[12:13], v[48:49] op_sel_hi:[1,0]
	v_pk_mul_f32 v[10:11], v[10:11], v[48:49] op_sel_hi:[1,0]
	v_pk_mul_f32 v[8:9], v[8:9], v[48:49] op_sel_hi:[1,0]
	v_pk_mul_f32 v[6:7], v[6:7], v[48:49] op_sel_hi:[1,0]
	v_pk_mul_f32 v[4:5], v[4:5], v[48:49] op_sel_hi:[1,0]
	v_pk_mul_f32 v[2:3], v[2:3], v[48:49] op_sel_hi:[1,0]
	s_branch .LBB0_643

.LBB0_653:
	s_waitcnt vmcnt(3)
	v_mfma_f32_32x32x16_bf16 v[34:49], v[74:77], v[62:65], 0
	v_lshl_add_u64 v[118:119], s[28:29], 0, v[98:99]
	s_waitcnt vmcnt(2)
	v_mfma_f32_32x32x16_bf16 v[34:49], v[70:73], v[58:61], v[34:49]
	v_lshl_add_u64 v[70:71], s[30:31], 0, v[98:99]
	v_add_co_u32_e32 v70, vcc, 0xc500000, v70
	s_nop 1
	v_addc_co_u32_e32 v71, vcc, 0, v71, vcc
	global_load_dwordx4 v[94:97], v[70:71], off
	global_load_dwordx4 v[90:93], v[70:71], off offset:1024
	global_load_dwordx4 v[82:85], v[70:71], off offset:2048
	global_load_dwordx4 v[86:89], v[70:71], off offset:3072
	s_waitcnt vmcnt(5)
	v_mfma_f32_32x32x16_bf16 v[34:49], v[66:69], v[54:57], v[34:49]
	global_load_dwordx4 v[74:77], v[118:119], off offset:-2048
	global_load_dwordx4 v[70:73], v[118:119], off offset:-1024
	s_waitcnt vmcnt(6)
	v_mfma_f32_32x32x16_bf16 v[34:49], v[78:81], v[50:53], v[34:49]
	global_load_dwordx4 v[66:69], v[118:119], off
	global_load_dwordx4 v[78:81], v[118:119], off offset:1024
	s_nop 9
	v_max_f32_e32 v0, v35, v35
	v_max_f32_e32 v117, v34, v34
	v_max_f32_e32 v0, v117, v0
	v_max_f32_e32 v117, v37, v37
	v_max_f32_e32 v118, v36, v36
	v_max_f32_e32 v117, v118, v117
	v_max_f32_e32 v118, v41, v41
	v_max_f32_e32 v119, v40, v40
	v_max_f32_e32 v118, v119, v118
	v_max3_f32 v118, v38, v39, v118
	v_max3_f32 v0, v0, v117, v118
	v_max_f32_e32 v117, v45, v45
	v_max_f32_e32 v118, v44, v44
	v_max_f32_e32 v117, v118, v117
	v_max_f32_e32 v118, v49, v49
	v_max_f32_e32 v119, v48, v48
	v_max_f32_e32 v118, v119, v118
	v_max3_f32 v117, v42, v43, v117
	v_max3_f32 v118, v46, v47, v118
	v_max3_f32 v0, v0, v117, v118
	v_mov_b32_e32 v117, v0
	s_nop 1
	v_permlane32_swap_b32_e32 v0, v117
	s_waitcnt lgkmcnt(0)
	v_max_f32_e32 v117, v117, v117
	v_max_f32_e32 v0, v0, v117
	v_cmp_gt_f32_e32 vcc, v0, v115
	s_cbranch_vccz .LBB0_652
	v_max_f32_e32 v0, v0, v0
	v_max_f32_e32 v117, v115, v115
	v_max_f32_e32 v117, v117, v0
	v_sub_f32_e32 v0, v115, v117
	v_exp_f32_e32 v0, v0
	v_mov_b32_e32 v115, v117
	v_mul_f32_e32 v116, v116, v0
	v_pk_mul_f32 v[32:33], v[32:33], v[0:1] op_sel_hi:[1,0]
	v_pk_mul_f32 v[30:31], v[30:31], v[0:1] op_sel_hi:[1,0]
	v_pk_mul_f32 v[28:29], v[28:29], v[0:1] op_sel_hi:[1,0]
	v_pk_mul_f32 v[26:27], v[26:27], v[0:1] op_sel_hi:[1,0]
	v_pk_mul_f32 v[24:25], v[24:25], v[0:1] op_sel_hi:[1,0]
	v_pk_mul_f32 v[22:23], v[22:23], v[0:1] op_sel_hi:[1,0]
	v_pk_mul_f32 v[20:21], v[20:21], v[0:1] op_sel_hi:[1,0]
	v_pk_mul_f32 v[18:19], v[18:19], v[0:1] op_sel_hi:[1,0]
	v_pk_mul_f32 v[16:17], v[16:17], v[0:1] op_sel_hi:[1,0]
	v_pk_mul_f32 v[14:15], v[14:15], v[0:1] op_sel_hi:[1,0]
	v_pk_mul_f32 v[12:13], v[12:13], v[0:1] op_sel_hi:[1,0]
	v_pk_mul_f32 v[10:11], v[10:11], v[0:1] op_sel_hi:[1,0]
	v_pk_mul_f32 v[8:9], v[8:9], v[0:1] op_sel_hi:[1,0]
	v_pk_mul_f32 v[6:7], v[6:7], v[0:1] op_sel_hi:[1,0]
	v_pk_mul_f32 v[4:5], v[4:5], v[0:1] op_sel_hi:[1,0]
	v_pk_mul_f32 v[2:3], v[2:3], v[0:1] op_sel_hi:[1,0]
	s_branch .LBB0_652
.LBB0_655:
	s_waitcnt vmcnt(3)
	v_mfma_f32_32x32x16_bf16 v[34:49], v[74:77], v[62:65], 0
	s_waitcnt vmcnt(2)
	v_mfma_f32_32x32x16_bf16 v[34:49], v[70:73], v[58:61], v[34:49]
	global_load_dwordx4 v[58:61], v[102:103], off
	global_load_dwordx4 v[62:65], v[104:105], off
	s_waitcnt vmcnt(3)
	v_mfma_f32_32x32x16_bf16 v[34:49], v[66:69], v[54:57], v[34:49]
	global_load_dwordx4 v[54:57], v[106:107], off
	global_load_dwordx4 v[66:69], v[108:109], off
	s_waitcnt vmcnt(4)
	v_mfma_f32_32x32x16_bf16 v[34:49], v[78:81], v[50:53], v[34:49]
	s_nop 11
	v_max_f32_e32 v0, v35, v35
	v_max_f32_e32 v50, v34, v34
	v_max_f32_e32 v0, v50, v0
	v_max_f32_e32 v50, v37, v37
	v_max_f32_e32 v51, v36, v36
	v_max_f32_e32 v50, v51, v50
	v_max_f32_e32 v51, v41, v41
	v_max_f32_e32 v52, v40, v40
	v_max_f32_e32 v51, v52, v51
	v_max3_f32 v51, v38, v39, v51
	v_max3_f32 v0, v0, v50, v51
	v_max_f32_e32 v50, v45, v45
	v_max_f32_e32 v51, v44, v44
	v_max_f32_e32 v50, v51, v50
	v_max_f32_e32 v51, v49, v49
	v_max_f32_e32 v52, v48, v48
	v_max_f32_e32 v51, v52, v51
	v_max3_f32 v50, v42, v43, v50
	v_max3_f32 v51, v46, v47, v51
	v_max3_f32 v0, v0, v50, v51
	v_mov_b32_e32 v50, v0
	s_nop 1
	v_permlane32_swap_b32_e32 v0, v50
	s_waitcnt lgkmcnt(0)
	v_max_f32_e32 v50, v50, v50
	v_max_f32_e32 v0, v0, v50
	v_cmp_gt_f32_e32 vcc, v0, v115
	s_cbranch_vccz .LBB0_650
	v_max_f32_e32 v0, v0, v0
	v_max_f32_e32 v50, v115, v115
	v_max_f32_e32 v50, v50, v0
	v_sub_f32_e32 v0, v115, v50
	v_exp_f32_e32 v0, v0
	v_mov_b32_e32 v115, v50
	v_mul_f32_e32 v116, v116, v0
	v_pk_mul_f32 v[32:33], v[32:33], v[0:1] op_sel_hi:[1,0]
	v_pk_mul_f32 v[30:31], v[30:31], v[0:1] op_sel_hi:[1,0]
	v_pk_mul_f32 v[28:29], v[28:29], v[0:1] op_sel_hi:[1,0]
	v_pk_mul_f32 v[26:27], v[26:27], v[0:1] op_sel_hi:[1,0]
	v_pk_mul_f32 v[24:25], v[24:25], v[0:1] op_sel_hi:[1,0]
	v_pk_mul_f32 v[22:23], v[22:23], v[0:1] op_sel_hi:[1,0]
	v_pk_mul_f32 v[20:21], v[20:21], v[0:1] op_sel_hi:[1,0]
	v_pk_mul_f32 v[18:19], v[18:19], v[0:1] op_sel_hi:[1,0]
	v_pk_mul_f32 v[16:17], v[16:17], v[0:1] op_sel_hi:[1,0]
	v_pk_mul_f32 v[14:15], v[14:15], v[0:1] op_sel_hi:[1,0]
	v_pk_mul_f32 v[12:13], v[12:13], v[0:1] op_sel_hi:[1,0]
	v_pk_mul_f32 v[10:11], v[10:11], v[0:1] op_sel_hi:[1,0]
	v_pk_mul_f32 v[8:9], v[8:9], v[0:1] op_sel_hi:[1,0]
	v_pk_mul_f32 v[6:7], v[6:7], v[0:1] op_sel_hi:[1,0]
	v_pk_mul_f32 v[4:5], v[4:5], v[0:1] op_sel_hi:[1,0]
	v_pk_mul_f32 v[2:3], v[2:3], v[0:1] op_sel_hi:[1,0]
	s_branch .LBB0_650

.LBB0_668:
	s_waitcnt vmcnt(3)
	v_mfma_f32_32x32x16_bf16 v[80:95], v[124:127], v[108:111], 0
	v_lshl_add_u64 v[2:3], s[24:25], 0, v[150:151]
	v_add_co_u32_e32 v4, vcc, 0xc500000, v2
	v_lshl_add_u64 v[14:15], s[18:19], 0, v[150:151]
	s_nop 0
	v_addc_co_u32_e32 v5, vcc, 0, v3, vcc
	v_add_co_u32_e32 v6, vcc, 0xc501000, v2
	s_waitcnt vmcnt(2)
	v_mfma_f32_32x32x16_bf16 v[80:95], v[120:123], v[104:107], v[80:95]
	v_addc_co_u32_e32 v7, vcc, 0, v3, vcc
	global_load_dwordx4 v[144:147], v[4:5], off
	global_load_dwordx4 v[128:131], v[4:5], off offset:1024
	global_load_dwordx4 v[136:139], v[4:5], off offset:2048
	global_load_dwordx4 v[140:143], v[4:5], off offset:3072
	global_load_dwordx4 v[132:135], v[6:7], off
	global_load_dwordx4 v[10:13], v[6:7], off offset:1024
	s_nop 0
	global_load_dwordx4 v[2:5], v[6:7], off offset:2048
	s_nop 0
	global_load_dwordx4 v[6:9], v[6:7], off offset:3072
	s_nop 0
	global_load_dwordx4 v[124:127], v[14:15], off offset:-2048
	global_load_dwordx4 v[120:123], v[14:15], off offset:-1024
	s_waitcnt vmcnt(11)
	v_mfma_f32_32x32x16_bf16 v[80:95], v[116:119], v[100:103], v[80:95]
	s_waitcnt vmcnt(10)
	v_mfma_f32_32x32x16_bf16 v[80:95], v[112:115], v[96:99], v[80:95]
	global_load_dwordx4 v[116:119], v[14:15], off
	global_load_dwordx4 v[112:115], v[14:15], off offset:1024
	s_nop 9
	v_max_f32_e32 v0, v81, v81
	v_max_f32_e32 v14, v80, v80
	v_max_f32_e32 v0, v14, v0
	v_max_f32_e32 v14, v83, v83
	v_max_f32_e32 v15, v82, v82
	v_max_f32_e32 v14, v15, v14
	v_max_f32_e32 v15, v87, v87
	v_max_f32_e32 v193, v86, v86
	v_max_f32_e32 v15, v193, v15
	v_max3_f32 v15, v84, v85, v15
	v_max3_f32 v0, v0, v14, v15
	v_max_f32_e32 v14, v91, v91
	v_max_f32_e32 v15, v90, v90
	v_max_f32_e32 v14, v15, v14
	v_max_f32_e32 v15, v95, v95
	v_max_f32_e32 v193, v94, v94
	v_max_f32_e32 v15, v193, v15
	v_max3_f32 v14, v88, v89, v14
	v_max3_f32 v15, v92, v93, v15
	v_max3_f32 v0, v0, v14, v15
	v_mov_b32_e32 v14, v0
	s_nop 1
	v_permlane32_swap_b32_e32 v0, v14
	s_waitcnt lgkmcnt(0)
	v_max_f32_e32 v14, v14, v14
	v_max_f32_e32 v0, v0, v14
	v_cmp_gt_f32_e32 vcc, v0, v192
	s_cbranch_vccz .LBB0_667
	v_max_f32_e32 v0, v0, v0
	v_max_f32_e32 v14, v192, v192
	v_max_f32_e32 v14, v14, v0
	v_sub_f32_e32 v0, v192, v14
	v_exp_f32_e32 v0, v0
	v_mov_b32_e32 v192, v14
	v_mul_f32_e32 v191, v191, v0
	v_pk_mul_f32 v[78:79], v[78:79], v[0:1] op_sel_hi:[1,0]
	v_pk_mul_f32 v[76:77], v[76:77], v[0:1] op_sel_hi:[1,0]
	v_pk_mul_f32 v[74:75], v[74:75], v[0:1] op_sel_hi:[1,0]
	v_pk_mul_f32 v[72:73], v[72:73], v[0:1] op_sel_hi:[1,0]
	v_pk_mul_f32 v[70:71], v[70:71], v[0:1] op_sel_hi:[1,0]
	v_pk_mul_f32 v[68:69], v[68:69], v[0:1] op_sel_hi:[1,0]
	v_pk_mul_f32 v[66:67], v[66:67], v[0:1] op_sel_hi:[1,0]
	v_pk_mul_f32 v[64:65], v[64:65], v[0:1] op_sel_hi:[1,0]
	v_pk_mul_f32 v[62:63], v[62:63], v[0:1] op_sel_hi:[1,0]
	v_pk_mul_f32 v[60:61], v[60:61], v[0:1] op_sel_hi:[1,0]
	v_pk_mul_f32 v[58:59], v[58:59], v[0:1] op_sel_hi:[1,0]
	v_pk_mul_f32 v[56:57], v[56:57], v[0:1] op_sel_hi:[1,0]
	v_pk_mul_f32 v[54:55], v[54:55], v[0:1] op_sel_hi:[1,0]
	v_pk_mul_f32 v[52:53], v[52:53], v[0:1] op_sel_hi:[1,0]
	v_pk_mul_f32 v[50:51], v[50:51], v[0:1] op_sel_hi:[1,0]
	v_pk_mul_f32 v[48:49], v[48:49], v[0:1] op_sel_hi:[1,0]
	v_pk_mul_f32 v[46:47], v[46:47], v[0:1] op_sel_hi:[1,0]
	v_pk_mul_f32 v[44:45], v[44:45], v[0:1] op_sel_hi:[1,0]
	v_pk_mul_f32 v[42:43], v[42:43], v[0:1] op_sel_hi:[1,0]
	v_pk_mul_f32 v[40:41], v[40:41], v[0:1] op_sel_hi:[1,0]
	v_pk_mul_f32 v[38:39], v[38:39], v[0:1] op_sel_hi:[1,0]
	v_pk_mul_f32 v[36:37], v[36:37], v[0:1] op_sel_hi:[1,0]
	v_pk_mul_f32 v[34:35], v[34:35], v[0:1] op_sel_hi:[1,0]
	v_pk_mul_f32 v[32:33], v[32:33], v[0:1] op_sel_hi:[1,0]
	v_pk_mul_f32 v[30:31], v[30:31], v[0:1] op_sel_hi:[1,0]
	v_pk_mul_f32 v[28:29], v[28:29], v[0:1] op_sel_hi:[1,0]
	v_pk_mul_f32 v[26:27], v[26:27], v[0:1] op_sel_hi:[1,0]
	v_pk_mul_f32 v[24:25], v[24:25], v[0:1] op_sel_hi:[1,0]
	v_pk_mul_f32 v[22:23], v[22:23], v[0:1] op_sel_hi:[1,0]
	v_pk_mul_f32 v[20:21], v[20:21], v[0:1] op_sel_hi:[1,0]
	v_pk_mul_f32 v[18:19], v[18:19], v[0:1] op_sel_hi:[1,0]
	v_pk_mul_f32 v[16:17], v[16:17], v[0:1] op_sel_hi:[1,0]
	s_branch .LBB0_667
.LBB0_670:
	s_waitcnt vmcnt(3)
	v_mfma_f32_32x32x16_bf16 v[80:95], v[124:127], v[108:111], 0
	s_waitcnt vmcnt(2)
	v_mfma_f32_32x32x16_bf16 v[80:95], v[120:123], v[104:107], v[80:95]
	global_load_dwordx4 v[128:131], v[172:173], off
	global_load_dwordx4 v[124:127], v[174:175], off
	global_load_dwordx4 v[120:123], v[176:177], off
	global_load_dwordx4 v[108:111], v[178:179], off
	global_load_dwordx4 v[104:107], v[180:181], off
	global_load_dwordx4 v[10:13], v[182:183], off
	global_load_dwordx4 v[6:9], v[184:185], off
	global_load_dwordx4 v[2:5], v[186:187], off
	s_waitcnt vmcnt(9)
	v_mfma_f32_32x32x16_bf16 v[80:95], v[116:119], v[100:103], v[80:95]
	s_waitcnt vmcnt(8)
	v_mfma_f32_32x32x16_bf16 v[80:95], v[112:115], v[96:99], v[80:95]
	s_nop 11
	v_max_f32_e32 v0, v81, v81
	v_max_f32_e32 v14, v80, v80
	v_max_f32_e32 v0, v14, v0
	v_max_f32_e32 v14, v83, v83
	v_max_f32_e32 v15, v82, v82
	v_max_f32_e32 v14, v15, v14
	v_max_f32_e32 v15, v87, v87
	v_max_f32_e32 v96, v86, v86
	v_max_f32_e32 v15, v96, v15
	v_max3_f32 v15, v84, v85, v15
	v_max3_f32 v0, v0, v14, v15
	v_max_f32_e32 v14, v91, v91
	v_max_f32_e32 v15, v90, v90
	v_max_f32_e32 v14, v15, v14
	v_max_f32_e32 v15, v95, v95
	v_max_f32_e32 v96, v94, v94
	v_max_f32_e32 v15, v96, v15
	v_max3_f32 v14, v88, v89, v14
	v_max3_f32 v15, v92, v93, v15
	v_max3_f32 v0, v0, v14, v15
	v_mov_b32_e32 v14, v0
	s_nop 1
	v_permlane32_swap_b32_e32 v0, v14
	s_waitcnt lgkmcnt(0)
	v_max_f32_e32 v14, v14, v14
	v_max_f32_e32 v0, v0, v14
	v_cmp_gt_f32_e32 vcc, v0, v192
	s_cbranch_vccz .LBB0_672
	v_max_f32_e32 v0, v0, v0
	v_max_f32_e32 v14, v192, v192
	v_max_f32_e32 v14, v14, v0
	v_sub_f32_e32 v0, v192, v14
	v_exp_f32_e32 v0, v0
	v_mov_b32_e32 v192, v14
	v_mul_f32_e32 v191, v191, v0
	v_pk_mul_f32 v[78:79], v[78:79], v[0:1] op_sel_hi:[1,0]
	v_pk_mul_f32 v[76:77], v[76:77], v[0:1] op_sel_hi:[1,0]
	v_pk_mul_f32 v[74:75], v[74:75], v[0:1] op_sel_hi:[1,0]
	v_pk_mul_f32 v[72:73], v[72:73], v[0:1] op_sel_hi:[1,0]
	v_pk_mul_f32 v[70:71], v[70:71], v[0:1] op_sel_hi:[1,0]
	v_pk_mul_f32 v[68:69], v[68:69], v[0:1] op_sel_hi:[1,0]
	v_pk_mul_f32 v[66:67], v[66:67], v[0:1] op_sel_hi:[1,0]
	v_pk_mul_f32 v[64:65], v[64:65], v[0:1] op_sel_hi:[1,0]
	v_pk_mul_f32 v[62:63], v[62:63], v[0:1] op_sel_hi:[1,0]
	v_pk_mul_f32 v[60:61], v[60:61], v[0:1] op_sel_hi:[1,0]
	v_pk_mul_f32 v[58:59], v[58:59], v[0:1] op_sel_hi:[1,0]
	v_pk_mul_f32 v[56:57], v[56:57], v[0:1] op_sel_hi:[1,0]
	v_pk_mul_f32 v[54:55], v[54:55], v[0:1] op_sel_hi:[1,0]
	v_pk_mul_f32 v[52:53], v[52:53], v[0:1] op_sel_hi:[1,0]
	v_pk_mul_f32 v[50:51], v[50:51], v[0:1] op_sel_hi:[1,0]
	v_pk_mul_f32 v[48:49], v[48:49], v[0:1] op_sel_hi:[1,0]
	v_pk_mul_f32 v[46:47], v[46:47], v[0:1] op_sel_hi:[1,0]
	v_pk_mul_f32 v[44:45], v[44:45], v[0:1] op_sel_hi:[1,0]
	v_pk_mul_f32 v[42:43], v[42:43], v[0:1] op_sel_hi:[1,0]
	v_pk_mul_f32 v[40:41], v[40:41], v[0:1] op_sel_hi:[1,0]
	v_pk_mul_f32 v[38:39], v[38:39], v[0:1] op_sel_hi:[1,0]
	v_pk_mul_f32 v[36:37], v[36:37], v[0:1] op_sel_hi:[1,0]
	v_pk_mul_f32 v[34:35], v[34:35], v[0:1] op_sel_hi:[1,0]
	v_pk_mul_f32 v[32:33], v[32:33], v[0:1] op_sel_hi:[1,0]
	v_pk_mul_f32 v[30:31], v[30:31], v[0:1] op_sel_hi:[1,0]
	v_pk_mul_f32 v[28:29], v[28:29], v[0:1] op_sel_hi:[1,0]
	v_pk_mul_f32 v[26:27], v[26:27], v[0:1] op_sel_hi:[1,0]
	v_pk_mul_f32 v[24:25], v[24:25], v[0:1] op_sel_hi:[1,0]
	v_pk_mul_f32 v[22:23], v[22:23], v[0:1] op_sel_hi:[1,0]
	v_pk_mul_f32 v[20:21], v[20:21], v[0:1] op_sel_hi:[1,0]
	v_pk_mul_f32 v[18:19], v[18:19], v[0:1] op_sel_hi:[1,0]
	v_pk_mul_f32 v[16:17], v[16:17], v[0:1] op_sel_hi:[1,0]

.LBB0_685:
	s_waitcnt vmcnt(3)
	v_mfma_f32_32x32x16_bf16 v[80:95], v[124:127], v[108:111], 0
	v_lshl_add_u64 v[2:3], s[26:27], 0, v[150:151]
	v_add_co_u32_e32 v4, vcc, 0xe500000, v2
	v_lshl_add_u64 v[14:15], s[24:25], 0, v[150:151]
	s_nop 0
	v_addc_co_u32_e32 v5, vcc, 0, v3, vcc
	v_add_co_u32_e32 v6, vcc, 0xe501000, v2
	s_waitcnt vmcnt(2)
	v_mfma_f32_32x32x16_bf16 v[80:95], v[120:123], v[104:107], v[80:95]
	v_addc_co_u32_e32 v7, vcc, 0, v3, vcc
	global_load_dwordx4 v[144:147], v[4:5], off
	global_load_dwordx4 v[128:131], v[4:5], off offset:1024
	global_load_dwordx4 v[136:139], v[4:5], off offset:2048
	global_load_dwordx4 v[140:143], v[4:5], off offset:3072
	global_load_dwordx4 v[132:135], v[6:7], off
	global_load_dwordx4 v[10:13], v[6:7], off offset:1024
	s_nop 0
	global_load_dwordx4 v[2:5], v[6:7], off offset:2048
	s_nop 0
	global_load_dwordx4 v[6:9], v[6:7], off offset:3072
	s_nop 0
	global_load_dwordx4 v[124:127], v[14:15], off offset:-2048
	global_load_dwordx4 v[120:123], v[14:15], off offset:-1024
	s_waitcnt vmcnt(11)
	v_mfma_f32_32x32x16_bf16 v[80:95], v[116:119], v[100:103], v[80:95]
	s_waitcnt vmcnt(10)
	v_mfma_f32_32x32x16_bf16 v[80:95], v[112:115], v[96:99], v[80:95]
	global_load_dwordx4 v[116:119], v[14:15], off
	global_load_dwordx4 v[112:115], v[14:15], off offset:1024
	s_nop 9
	v_max_f32_e32 v0, v81, v81
	v_max_f32_e32 v14, v80, v80
	v_max_f32_e32 v0, v14, v0
	v_max_f32_e32 v14, v83, v83
	v_max_f32_e32 v15, v82, v82
	v_max_f32_e32 v14, v15, v14
	v_max_f32_e32 v15, v87, v87
	v_max_f32_e32 v219, v86, v86
	v_max_f32_e32 v15, v219, v15
	v_max3_f32 v15, v84, v85, v15
	v_max3_f32 v0, v0, v14, v15
	v_max_f32_e32 v14, v91, v91
	v_max_f32_e32 v15, v90, v90
	v_max_f32_e32 v14, v15, v14
	v_max_f32_e32 v15, v95, v95
	v_max_f32_e32 v219, v94, v94
	v_max_f32_e32 v15, v219, v15
	v_max3_f32 v14, v88, v89, v14
	v_max3_f32 v15, v92, v93, v15
	v_max3_f32 v0, v0, v14, v15
	v_mov_b32_e32 v14, v0
	s_nop 1
	v_permlane32_swap_b32_e32 v0, v14
	s_waitcnt lgkmcnt(0)
	v_max_f32_e32 v14, v14, v14
	v_max_f32_e32 v0, v0, v14
	v_cmp_gt_f32_e32 vcc, v0, v171
	s_cbranch_vccz .LBB0_684
	v_max_f32_e32 v0, v0, v0
	v_max_f32_e32 v14, v171, v171
	v_max_f32_e32 v14, v14, v0
	v_sub_f32_e32 v0, v171, v14
	v_exp_f32_e32 v0, v0
	v_mov_b32_e32 v171, v14
	v_mul_f32_e32 v218, v218, v0
	v_pk_mul_f32 v[78:79], v[78:79], v[0:1] op_sel_hi:[1,0]
	v_pk_mul_f32 v[76:77], v[76:77], v[0:1] op_sel_hi:[1,0]
	v_pk_mul_f32 v[74:75], v[74:75], v[0:1] op_sel_hi:[1,0]
	v_pk_mul_f32 v[72:73], v[72:73], v[0:1] op_sel_hi:[1,0]
	v_pk_mul_f32 v[70:71], v[70:71], v[0:1] op_sel_hi:[1,0]
	v_pk_mul_f32 v[68:69], v[68:69], v[0:1] op_sel_hi:[1,0]
	v_pk_mul_f32 v[66:67], v[66:67], v[0:1] op_sel_hi:[1,0]
	v_pk_mul_f32 v[64:65], v[64:65], v[0:1] op_sel_hi:[1,0]
	v_pk_mul_f32 v[62:63], v[62:63], v[0:1] op_sel_hi:[1,0]
	v_pk_mul_f32 v[60:61], v[60:61], v[0:1] op_sel_hi:[1,0]
	v_pk_mul_f32 v[58:59], v[58:59], v[0:1] op_sel_hi:[1,0]
	v_pk_mul_f32 v[56:57], v[56:57], v[0:1] op_sel_hi:[1,0]
	v_pk_mul_f32 v[54:55], v[54:55], v[0:1] op_sel_hi:[1,0]
	v_pk_mul_f32 v[52:53], v[52:53], v[0:1] op_sel_hi:[1,0]
	v_pk_mul_f32 v[50:51], v[50:51], v[0:1] op_sel_hi:[1,0]
	v_pk_mul_f32 v[48:49], v[48:49], v[0:1] op_sel_hi:[1,0]
	v_pk_mul_f32 v[46:47], v[46:47], v[0:1] op_sel_hi:[1,0]
	v_pk_mul_f32 v[44:45], v[44:45], v[0:1] op_sel_hi:[1,0]
	v_pk_mul_f32 v[42:43], v[42:43], v[0:1] op_sel_hi:[1,0]
	v_pk_mul_f32 v[40:41], v[40:41], v[0:1] op_sel_hi:[1,0]
	v_pk_mul_f32 v[38:39], v[38:39], v[0:1] op_sel_hi:[1,0]
	v_pk_mul_f32 v[36:37], v[36:37], v[0:1] op_sel_hi:[1,0]
	v_pk_mul_f32 v[34:35], v[34:35], v[0:1] op_sel_hi:[1,0]
	v_pk_mul_f32 v[32:33], v[32:33], v[0:1] op_sel_hi:[1,0]
	v_pk_mul_f32 v[30:31], v[30:31], v[0:1] op_sel_hi:[1,0]
	v_pk_mul_f32 v[28:29], v[28:29], v[0:1] op_sel_hi:[1,0]
	v_pk_mul_f32 v[26:27], v[26:27], v[0:1] op_sel_hi:[1,0]
	v_pk_mul_f32 v[24:25], v[24:25], v[0:1] op_sel_hi:[1,0]
	v_pk_mul_f32 v[22:23], v[22:23], v[0:1] op_sel_hi:[1,0]
	v_pk_mul_f32 v[20:21], v[20:21], v[0:1] op_sel_hi:[1,0]
	v_pk_mul_f32 v[18:19], v[18:19], v[0:1] op_sel_hi:[1,0]
	v_pk_mul_f32 v[16:17], v[16:17], v[0:1] op_sel_hi:[1,0]
	s_branch .LBB0_684
.LBB0_687:
	s_waitcnt vmcnt(3)
	v_mfma_f32_32x32x16_bf16 v[80:95], v[124:127], v[108:111], 0
	s_waitcnt vmcnt(2)
	v_mfma_f32_32x32x16_bf16 v[80:95], v[120:123], v[104:107], v[80:95]
	global_load_dwordx4 v[132:135], v[176:177], off
	global_load_dwordx4 v[124:127], v[178:179], off
	global_load_dwordx4 v[120:123], v[180:181], off
	global_load_dwordx4 v[10:13], v[182:183], off
	global_load_dwordx4 v[2:5], v[184:185], off
	global_load_dwordx4 v[6:9], v[186:187], off
	s_waitcnt vmcnt(7)
	v_mfma_f32_32x32x16_bf16 v[80:95], v[116:119], v[100:103], v[80:95]
	global_load_dwordx4 v[116:119], v[188:189], off
	global_load_dwordx4 v[128:131], v[190:191], off
	s_waitcnt vmcnt(8)
	v_mfma_f32_32x32x16_bf16 v[80:95], v[112:115], v[96:99], v[80:95]
	s_nop 11
	v_max_f32_e32 v0, v81, v81
	v_max_f32_e32 v14, v80, v80
	v_max_f32_e32 v0, v14, v0
	v_max_f32_e32 v14, v83, v83
	v_max_f32_e32 v15, v82, v82
	v_max_f32_e32 v14, v15, v14
	v_max_f32_e32 v15, v87, v87
	v_max_f32_e32 v112, v86, v86
	v_max_f32_e32 v15, v112, v15
	v_max3_f32 v15, v84, v85, v15
	v_max3_f32 v0, v0, v14, v15
	v_max_f32_e32 v14, v91, v91
	v_max_f32_e32 v15, v90, v90
	v_max_f32_e32 v14, v15, v14
	v_max_f32_e32 v15, v95, v95
	v_max_f32_e32 v112, v94, v94
	v_max_f32_e32 v15, v112, v15
	v_max3_f32 v14, v88, v89, v14
	v_max3_f32 v15, v92, v93, v15
	v_max3_f32 v0, v0, v14, v15
	v_mov_b32_e32 v14, v0
	s_nop 1
	v_permlane32_swap_b32_e32 v0, v14
	s_waitcnt lgkmcnt(0)
	v_max_f32_e32 v14, v14, v14
	v_max_f32_e32 v0, v0, v14
	v_cmp_gt_f32_e32 vcc, v0, v171
	s_cbranch_vccz .LBB0_689
	v_max_f32_e32 v0, v0, v0
	v_max_f32_e32 v14, v171, v171
	v_max_f32_e32 v14, v14, v0
	v_sub_f32_e32 v0, v171, v14
	v_exp_f32_e32 v0, v0
	v_mov_b32_e32 v171, v14
	v_mul_f32_e32 v218, v218, v0
	v_pk_mul_f32 v[78:79], v[78:79], v[0:1] op_sel_hi:[1,0]
	v_pk_mul_f32 v[76:77], v[76:77], v[0:1] op_sel_hi:[1,0]
	v_pk_mul_f32 v[74:75], v[74:75], v[0:1] op_sel_hi:[1,0]
	v_pk_mul_f32 v[72:73], v[72:73], v[0:1] op_sel_hi:[1,0]
	v_pk_mul_f32 v[70:71], v[70:71], v[0:1] op_sel_hi:[1,0]
	v_pk_mul_f32 v[68:69], v[68:69], v[0:1] op_sel_hi:[1,0]
	v_pk_mul_f32 v[66:67], v[66:67], v[0:1] op_sel_hi:[1,0]
	v_pk_mul_f32 v[64:65], v[64:65], v[0:1] op_sel_hi:[1,0]
	v_pk_mul_f32 v[62:63], v[62:63], v[0:1] op_sel_hi:[1,0]
	v_pk_mul_f32 v[60:61], v[60:61], v[0:1] op_sel_hi:[1,0]
	v_pk_mul_f32 v[58:59], v[58:59], v[0:1] op_sel_hi:[1,0]
	v_pk_mul_f32 v[56:57], v[56:57], v[0:1] op_sel_hi:[1,0]
	v_pk_mul_f32 v[54:55], v[54:55], v[0:1] op_sel_hi:[1,0]
	v_pk_mul_f32 v[52:53], v[52:53], v[0:1] op_sel_hi:[1,0]
	v_pk_mul_f32 v[50:51], v[50:51], v[0:1] op_sel_hi:[1,0]
	v_pk_mul_f32 v[48:49], v[48:49], v[0:1] op_sel_hi:[1,0]
	v_pk_mul_f32 v[46:47], v[46:47], v[0:1] op_sel_hi:[1,0]
	v_pk_mul_f32 v[44:45], v[44:45], v[0:1] op_sel_hi:[1,0]
	v_pk_mul_f32 v[42:43], v[42:43], v[0:1] op_sel_hi:[1,0]
	v_pk_mul_f32 v[40:41], v[40:41], v[0:1] op_sel_hi:[1,0]
	v_pk_mul_f32 v[38:39], v[38:39], v[0:1] op_sel_hi:[1,0]
	v_pk_mul_f32 v[36:37], v[36:37], v[0:1] op_sel_hi:[1,0]
	v_pk_mul_f32 v[34:35], v[34:35], v[0:1] op_sel_hi:[1,0]
	v_pk_mul_f32 v[32:33], v[32:33], v[0:1] op_sel_hi:[1,0]
	v_pk_mul_f32 v[30:31], v[30:31], v[0:1] op_sel_hi:[1,0]
	v_pk_mul_f32 v[28:29], v[28:29], v[0:1] op_sel_hi:[1,0]
	v_pk_mul_f32 v[26:27], v[26:27], v[0:1] op_sel_hi:[1,0]
	v_pk_mul_f32 v[24:25], v[24:25], v[0:1] op_sel_hi:[1,0]
	v_pk_mul_f32 v[22:23], v[22:23], v[0:1] op_sel_hi:[1,0]
	v_pk_mul_f32 v[20:21], v[20:21], v[0:1] op_sel_hi:[1,0]
	v_pk_mul_f32 v[18:19], v[18:19], v[0:1] op_sel_hi:[1,0]
	v_pk_mul_f32 v[16:17], v[16:17], v[0:1] op_sel_hi:[1,0]

.LBB0_691:
	s_waitcnt vmcnt(3)
	v_mfma_f32_32x32x16_bf16 v[80:95], v[112:115], v[108:111], 0
	v_lshl_add_u64 v[14:15], s[24:25], 0, v[150:151]
	v_add_co_u32_e32 v112, vcc, 0xe510000, v14
	s_nop 1
	v_addc_co_u32_e32 v113, vcc, 0, v15, vcc
	global_load_dwordx4 v[144:147], v[112:113], off
	global_load_dwordx4 v[128:131], v[112:113], off offset:1024
	s_waitcnt vmcnt(4)
	v_mfma_f32_32x32x16_bf16 v[80:95], v[10:13], v[104:107], v[80:95]
	v_add_co_u32_e32 v10, vcc, 0xe511000, v14
	global_load_dwordx4 v[136:139], v[112:113], off offset:2048
	global_load_dwordx4 v[140:143], v[112:113], off offset:3072
	v_addc_co_u32_e32 v11, vcc, 0, v15, vcc
	global_load_dwordx4 v[132:135], v[10:11], off
	global_load_dwordx4 v[124:127], v[10:11], off offset:1024
	global_load_dwordx4 v[116:119], v[10:11], off offset:2048
	global_load_dwordx4 v[120:123], v[10:11], off offset:3072
	v_lshl_add_u64 v[14:15], s[18:19], 0, v[150:151]
	s_waitcnt vmcnt(9)
	v_mfma_f32_32x32x16_bf16 v[80:95], v[6:9], v[100:103], v[80:95]
	global_load_dwordx4 v[112:115], v[14:15], off offset:-2048
	global_load_dwordx4 v[10:13], v[14:15], off offset:-1024
	s_waitcnt vmcnt(10)
	v_mfma_f32_32x32x16_bf16 v[80:95], v[2:5], v[96:99], v[80:95]
	global_load_dwordx4 v[6:9], v[14:15], off
	global_load_dwordx4 v[2:5], v[14:15], off offset:1024
	s_nop 9
	v_max_f32_e32 v14, v81, v81
	v_max_f32_e32 v15, v80, v80
	v_max_f32_e32 v14, v15, v14
	v_max_f32_e32 v15, v83, v83
	v_max_f32_e32 v218, v82, v82
	v_max_f32_e32 v15, v218, v15
	v_max_f32_e32 v218, v87, v87
	v_max_f32_e32 v219, v86, v86
	v_max_f32_e32 v218, v219, v218
	v_max3_f32 v218, v84, v85, v218
	v_max3_f32 v14, v14, v15, v218
	v_max_f32_e32 v15, v91, v91
	v_max_f32_e32 v218, v90, v90
	v_max_f32_e32 v15, v218, v15
	v_max_f32_e32 v218, v95, v95
	v_max_f32_e32 v219, v94, v94
	v_max_f32_e32 v218, v219, v218
	v_max3_f32 v15, v88, v89, v15
	v_max3_f32 v218, v92, v93, v218
	v_max3_f32 v14, v14, v15, v218
	v_mov_b32_e32 v15, v14
	s_nop 1
	v_permlane32_swap_b32_e32 v14, v15
	s_waitcnt lgkmcnt(0)
	v_max_f32_e32 v15, v15, v15
	v_max_f32_e32 v14, v14, v15
	v_cmp_gt_f32_e32 vcc, v14, v171
	s_cbranch_vccz .LBB0_690
	v_max_f32_e32 v14, v14, v14
	v_max_f32_e32 v15, v171, v171
	v_max_f32_e32 v15, v15, v14
	v_sub_f32_e32 v14, v171, v15
	v_exp_f32_e32 v14, v14
	v_mov_b32_e32 v171, v15
	v_mul_f32_e32 v0, v0, v14
	v_pk_mul_f32 v[78:79], v[78:79], v[14:15] op_sel_hi:[1,0]
	v_pk_mul_f32 v[76:77], v[76:77], v[14:15] op_sel_hi:[1,0]
	v_pk_mul_f32 v[74:75], v[74:75], v[14:15] op_sel_hi:[1,0]
	v_pk_mul_f32 v[72:73], v[72:73], v[14:15] op_sel_hi:[1,0]
	v_pk_mul_f32 v[70:71], v[70:71], v[14:15] op_sel_hi:[1,0]
	v_pk_mul_f32 v[68:69], v[68:69], v[14:15] op_sel_hi:[1,0]
	v_pk_mul_f32 v[66:67], v[66:67], v[14:15] op_sel_hi:[1,0]
	v_pk_mul_f32 v[64:65], v[64:65], v[14:15] op_sel_hi:[1,0]
	v_pk_mul_f32 v[62:63], v[62:63], v[14:15] op_sel_hi:[1,0]
	v_pk_mul_f32 v[60:61], v[60:61], v[14:15] op_sel_hi:[1,0]
	v_pk_mul_f32 v[58:59], v[58:59], v[14:15] op_sel_hi:[1,0]
	v_pk_mul_f32 v[56:57], v[56:57], v[14:15] op_sel_hi:[1,0]
	v_pk_mul_f32 v[54:55], v[54:55], v[14:15] op_sel_hi:[1,0]
	v_pk_mul_f32 v[52:53], v[52:53], v[14:15] op_sel_hi:[1,0]
	v_pk_mul_f32 v[50:51], v[50:51], v[14:15] op_sel_hi:[1,0]
	v_pk_mul_f32 v[48:49], v[48:49], v[14:15] op_sel_hi:[1,0]
	v_pk_mul_f32 v[46:47], v[46:47], v[14:15] op_sel_hi:[1,0]
	v_pk_mul_f32 v[44:45], v[44:45], v[14:15] op_sel_hi:[1,0]
	v_pk_mul_f32 v[42:43], v[42:43], v[14:15] op_sel_hi:[1,0]
	v_pk_mul_f32 v[40:41], v[40:41], v[14:15] op_sel_hi:[1,0]
	v_pk_mul_f32 v[38:39], v[38:39], v[14:15] op_sel_hi:[1,0]
	v_pk_mul_f32 v[36:37], v[36:37], v[14:15] op_sel_hi:[1,0]
	v_pk_mul_f32 v[34:35], v[34:35], v[14:15] op_sel_hi:[1,0]
	v_pk_mul_f32 v[32:33], v[32:33], v[14:15] op_sel_hi:[1,0]
	v_pk_mul_f32 v[30:31], v[30:31], v[14:15] op_sel_hi:[1,0]
	v_pk_mul_f32 v[28:29], v[28:29], v[14:15] op_sel_hi:[1,0]
	v_pk_mul_f32 v[26:27], v[26:27], v[14:15] op_sel_hi:[1,0]
	v_pk_mul_f32 v[24:25], v[24:25], v[14:15] op_sel_hi:[1,0]
	v_pk_mul_f32 v[22:23], v[22:23], v[14:15] op_sel_hi:[1,0]
	v_pk_mul_f32 v[20:21], v[20:21], v[14:15] op_sel_hi:[1,0]
	v_pk_mul_f32 v[18:19], v[18:19], v[14:15] op_sel_hi:[1,0]
	v_pk_mul_f32 v[16:17], v[16:17], v[14:15] op_sel_hi:[1,0]
	s_branch .LBB0_690
.LBB0_693:
	s_waitcnt vmcnt(3)
	v_mfma_f32_32x32x16_bf16 v[80:95], v[112:115], v[108:111], 0
	s_waitcnt vmcnt(2)
	v_mfma_f32_32x32x16_bf16 v[80:95], v[10:13], v[104:107], v[80:95]
	global_load_dwordx4 v[124:127], v[192:193], off
	global_load_dwordx4 v[120:123], v[196:197], off
	global_load_dwordx4 v[116:119], v[198:199], off
	global_load_dwordx4 v[112:115], v[200:201], off
	global_load_dwordx4 v[108:111], v[202:203], off
	global_load_dwordx4 v[104:107], v[204:205], off
	s_waitcnt vmcnt(7)
	v_mfma_f32_32x32x16_bf16 v[80:95], v[6:9], v[100:103], v[80:95]
	global_load_dwordx4 v[10:13], v[206:207], off
	global_load_dwordx4 v[6:9], v[208:209], off
	s_waitcnt vmcnt(8)
	v_mfma_f32_32x32x16_bf16 v[80:95], v[2:5], v[96:99], v[80:95]
	s_nop 11
	v_max_f32_e32 v2, v81, v81
	v_max_f32_e32 v3, v80, v80
	v_max_f32_e32 v2, v3, v2
	v_max_f32_e32 v3, v83, v83
	v_max_f32_e32 v4, v82, v82
	v_max_f32_e32 v3, v4, v3
	v_max_f32_e32 v4, v87, v87
	v_max_f32_e32 v5, v86, v86
	v_max_f32_e32 v4, v5, v4
	v_max3_f32 v4, v84, v85, v4
	v_max3_f32 v2, v2, v3, v4
	v_max_f32_e32 v3, v91, v91
	v_max_f32_e32 v4, v90, v90
	v_max_f32_e32 v3, v4, v3
	v_max_f32_e32 v4, v95, v95
	v_max_f32_e32 v5, v94, v94
	v_max_f32_e32 v4, v5, v4
	v_max3_f32 v3, v88, v89, v3
	v_max3_f32 v4, v92, v93, v4
	v_max3_f32 v2, v2, v3, v4
	v_mov_b32_e32 v3, v2
	s_nop 1
	v_permlane32_swap_b32_e32 v2, v3
	s_waitcnt lgkmcnt(0)
	v_max_f32_e32 v3, v3, v3
	v_max_f32_e32 v2, v2, v3
	v_cmp_gt_f32_e32 vcc, v2, v171
	s_cbranch_vccz .LBB0_695
	v_max_f32_e32 v2, v2, v2
	v_max_f32_e32 v3, v171, v171
	v_max_f32_e32 v3, v3, v2
	v_sub_f32_e32 v2, v171, v3
	v_exp_f32_e32 v2, v2
	v_mov_b32_e32 v171, v3
	v_mul_f32_e32 v0, v0, v2
	v_pk_mul_f32 v[78:79], v[78:79], v[2:3] op_sel_hi:[1,0]
	v_pk_mul_f32 v[76:77], v[76:77], v[2:3] op_sel_hi:[1,0]
	v_pk_mul_f32 v[74:75], v[74:75], v[2:3] op_sel_hi:[1,0]
	v_pk_mul_f32 v[72:73], v[72:73], v[2:3] op_sel_hi:[1,0]
	v_pk_mul_f32 v[70:71], v[70:71], v[2:3] op_sel_hi:[1,0]
	v_pk_mul_f32 v[68:69], v[68:69], v[2:3] op_sel_hi:[1,0]
	v_pk_mul_f32 v[66:67], v[66:67], v[2:3] op_sel_hi:[1,0]
	v_pk_mul_f32 v[64:65], v[64:65], v[2:3] op_sel_hi:[1,0]
	v_pk_mul_f32 v[62:63], v[62:63], v[2:3] op_sel_hi:[1,0]
	v_pk_mul_f32 v[60:61], v[60:61], v[2:3] op_sel_hi:[1,0]
	v_pk_mul_f32 v[58:59], v[58:59], v[2:3] op_sel_hi:[1,0]
	v_pk_mul_f32 v[56:57], v[56:57], v[2:3] op_sel_hi:[1,0]
	v_pk_mul_f32 v[54:55], v[54:55], v[2:3] op_sel_hi:[1,0]
	v_pk_mul_f32 v[52:53], v[52:53], v[2:3] op_sel_hi:[1,0]
	v_pk_mul_f32 v[50:51], v[50:51], v[2:3] op_sel_hi:[1,0]
	v_pk_mul_f32 v[48:49], v[48:49], v[2:3] op_sel_hi:[1,0]
	v_pk_mul_f32 v[46:47], v[46:47], v[2:3] op_sel_hi:[1,0]
	v_pk_mul_f32 v[44:45], v[44:45], v[2:3] op_sel_hi:[1,0]
	v_pk_mul_f32 v[42:43], v[42:43], v[2:3] op_sel_hi:[1,0]
	v_pk_mul_f32 v[40:41], v[40:41], v[2:3] op_sel_hi:[1,0]
	v_pk_mul_f32 v[38:39], v[38:39], v[2:3] op_sel_hi:[1,0]
	v_pk_mul_f32 v[36:37], v[36:37], v[2:3] op_sel_hi:[1,0]
	v_pk_mul_f32 v[34:35], v[34:35], v[2:3] op_sel_hi:[1,0]
	v_pk_mul_f32 v[32:33], v[32:33], v[2:3] op_sel_hi:[1,0]
	v_pk_mul_f32 v[30:31], v[30:31], v[2:3] op_sel_hi:[1,0]
	v_pk_mul_f32 v[28:29], v[28:29], v[2:3] op_sel_hi:[1,0]
	v_pk_mul_f32 v[26:27], v[26:27], v[2:3] op_sel_hi:[1,0]
	v_pk_mul_f32 v[24:25], v[24:25], v[2:3] op_sel_hi:[1,0]
	v_pk_mul_f32 v[22:23], v[22:23], v[2:3] op_sel_hi:[1,0]
	v_pk_mul_f32 v[20:21], v[20:21], v[2:3] op_sel_hi:[1,0]
	v_pk_mul_f32 v[18:19], v[18:19], v[2:3] op_sel_hi:[1,0]
	v_pk_mul_f32 v[16:17], v[16:17], v[2:3] op_sel_hi:[1,0]

.LBB0_707:
	s_waitcnt vmcnt(3)
	v_mfma_f32_32x32x16_bf16 v[80:95], v[124:127], v[108:111], 0
	v_lshl_add_u64 v[2:3], s[28:29], 0, v[150:151]
	v_add_co_u32_e32 v4, vcc, 0xe500000, v2
	v_lshl_add_u64 v[14:15], s[26:27], 0, v[150:151]
	s_nop 0
	v_addc_co_u32_e32 v5, vcc, 0, v3, vcc
	v_add_co_u32_e32 v6, vcc, 0xe501000, v2
	s_waitcnt vmcnt(2)
	v_mfma_f32_32x32x16_bf16 v[80:95], v[120:123], v[104:107], v[80:95]
	v_addc_co_u32_e32 v7, vcc, 0, v3, vcc
	global_load_dwordx4 v[144:147], v[4:5], off
	global_load_dwordx4 v[128:131], v[4:5], off offset:1024
	global_load_dwordx4 v[136:139], v[4:5], off offset:2048
	global_load_dwordx4 v[140:143], v[4:5], off offset:3072
	global_load_dwordx4 v[132:135], v[6:7], off
	global_load_dwordx4 v[10:13], v[6:7], off offset:1024
	s_nop 0
	global_load_dwordx4 v[2:5], v[6:7], off offset:2048
	s_nop 0
	global_load_dwordx4 v[6:9], v[6:7], off offset:3072
	s_nop 0
	global_load_dwordx4 v[124:127], v[14:15], off offset:-2048
	global_load_dwordx4 v[120:123], v[14:15], off offset:-1024
	s_waitcnt vmcnt(11)
	v_mfma_f32_32x32x16_bf16 v[80:95], v[116:119], v[100:103], v[80:95]
	s_waitcnt vmcnt(10)
	v_mfma_f32_32x32x16_bf16 v[80:95], v[112:115], v[96:99], v[80:95]
	global_load_dwordx4 v[116:119], v[14:15], off
	global_load_dwordx4 v[112:115], v[14:15], off offset:1024
	s_nop 9
	v_max_f32_e32 v0, v81, v81
	v_max_f32_e32 v14, v80, v80
	v_max_f32_e32 v0, v14, v0
	v_max_f32_e32 v14, v83, v83
	v_max_f32_e32 v15, v82, v82
	v_max_f32_e32 v14, v15, v14
	v_max_f32_e32 v15, v87, v87
	v_max_f32_e32 v212, v86, v86
	v_max_f32_e32 v15, v212, v15
	v_max3_f32 v15, v84, v85, v15
	v_max3_f32 v0, v0, v14, v15
	v_max_f32_e32 v14, v91, v91
	v_max_f32_e32 v15, v90, v90
	v_max_f32_e32 v14, v15, v14
	v_max_f32_e32 v15, v95, v95
	v_max_f32_e32 v212, v94, v94
	v_max_f32_e32 v15, v212, v15
	v_max3_f32 v14, v88, v89, v14
	v_max3_f32 v15, v92, v93, v15
	v_max3_f32 v0, v0, v14, v15
	v_mov_b32_e32 v14, v0
	s_nop 1
	v_permlane32_swap_b32_e32 v0, v14
	s_waitcnt lgkmcnt(0)
	v_max_f32_e32 v14, v14, v14
	v_max_f32_e32 v0, v0, v14
	v_cmp_gt_f32_e32 vcc, v0, v208
	s_cbranch_vccz .LBB0_706
	v_max_f32_e32 v0, v0, v0
	v_max_f32_e32 v14, v208, v208
	v_max_f32_e32 v14, v14, v0
	v_sub_f32_e32 v0, v208, v14
	v_exp_f32_e32 v0, v0
	v_mov_b32_e32 v208, v14
	v_mul_f32_e32 v209, v209, v0
	v_pk_mul_f32 v[78:79], v[78:79], v[0:1] op_sel_hi:[1,0]
	v_pk_mul_f32 v[76:77], v[76:77], v[0:1] op_sel_hi:[1,0]
	v_pk_mul_f32 v[74:75], v[74:75], v[0:1] op_sel_hi:[1,0]
	v_pk_mul_f32 v[72:73], v[72:73], v[0:1] op_sel_hi:[1,0]
	v_pk_mul_f32 v[70:71], v[70:71], v[0:1] op_sel_hi:[1,0]
	v_pk_mul_f32 v[68:69], v[68:69], v[0:1] op_sel_hi:[1,0]
	v_pk_mul_f32 v[66:67], v[66:67], v[0:1] op_sel_hi:[1,0]
	v_pk_mul_f32 v[64:65], v[64:65], v[0:1] op_sel_hi:[1,0]
	v_pk_mul_f32 v[62:63], v[62:63], v[0:1] op_sel_hi:[1,0]
	v_pk_mul_f32 v[60:61], v[60:61], v[0:1] op_sel_hi:[1,0]
	v_pk_mul_f32 v[58:59], v[58:59], v[0:1] op_sel_hi:[1,0]
	v_pk_mul_f32 v[56:57], v[56:57], v[0:1] op_sel_hi:[1,0]
	v_pk_mul_f32 v[54:55], v[54:55], v[0:1] op_sel_hi:[1,0]
	v_pk_mul_f32 v[52:53], v[52:53], v[0:1] op_sel_hi:[1,0]
	v_pk_mul_f32 v[50:51], v[50:51], v[0:1] op_sel_hi:[1,0]
	v_pk_mul_f32 v[48:49], v[48:49], v[0:1] op_sel_hi:[1,0]
	v_pk_mul_f32 v[46:47], v[46:47], v[0:1] op_sel_hi:[1,0]
	v_pk_mul_f32 v[44:45], v[44:45], v[0:1] op_sel_hi:[1,0]
	v_pk_mul_f32 v[42:43], v[42:43], v[0:1] op_sel_hi:[1,0]
	v_pk_mul_f32 v[40:41], v[40:41], v[0:1] op_sel_hi:[1,0]
	v_pk_mul_f32 v[38:39], v[38:39], v[0:1] op_sel_hi:[1,0]
	v_pk_mul_f32 v[36:37], v[36:37], v[0:1] op_sel_hi:[1,0]
	v_pk_mul_f32 v[34:35], v[34:35], v[0:1] op_sel_hi:[1,0]
	v_pk_mul_f32 v[32:33], v[32:33], v[0:1] op_sel_hi:[1,0]
	v_pk_mul_f32 v[30:31], v[30:31], v[0:1] op_sel_hi:[1,0]
	v_pk_mul_f32 v[28:29], v[28:29], v[0:1] op_sel_hi:[1,0]
	v_pk_mul_f32 v[26:27], v[26:27], v[0:1] op_sel_hi:[1,0]
	v_pk_mul_f32 v[24:25], v[24:25], v[0:1] op_sel_hi:[1,0]
	v_pk_mul_f32 v[22:23], v[22:23], v[0:1] op_sel_hi:[1,0]
	v_pk_mul_f32 v[20:21], v[20:21], v[0:1] op_sel_hi:[1,0]
	v_pk_mul_f32 v[18:19], v[18:19], v[0:1] op_sel_hi:[1,0]
	v_pk_mul_f32 v[16:17], v[16:17], v[0:1] op_sel_hi:[1,0]
	s_branch .LBB0_706
.LBB0_709:
	s_waitcnt vmcnt(3)
	v_mfma_f32_32x32x16_bf16 v[80:95], v[124:127], v[108:111], 0
	s_waitcnt vmcnt(2)
	v_mfma_f32_32x32x16_bf16 v[80:95], v[120:123], v[104:107], v[80:95]
	global_load_dwordx4 v[132:135], v[156:157], off
	global_load_dwordx4 v[124:127], v[158:159], off
	global_load_dwordx4 v[120:123], v[160:161], off
	global_load_dwordx4 v[10:13], v[162:163], off
	global_load_dwordx4 v[2:5], v[164:165], off
	global_load_dwordx4 v[6:9], v[166:167], off
	s_waitcnt vmcnt(7)
	v_mfma_f32_32x32x16_bf16 v[80:95], v[116:119], v[100:103], v[80:95]
	global_load_dwordx4 v[116:119], v[168:169], off
	global_load_dwordx4 v[128:131], v[170:171], off
	s_waitcnt vmcnt(8)
	v_mfma_f32_32x32x16_bf16 v[80:95], v[112:115], v[96:99], v[80:95]
	s_nop 11
	v_max_f32_e32 v0, v81, v81
	v_max_f32_e32 v14, v80, v80
	v_max_f32_e32 v0, v14, v0
	v_max_f32_e32 v14, v83, v83
	v_max_f32_e32 v15, v82, v82
	v_max_f32_e32 v14, v15, v14
	v_max_f32_e32 v15, v87, v87
	v_max_f32_e32 v112, v86, v86
	v_max_f32_e32 v15, v112, v15
	v_max3_f32 v15, v84, v85, v15
	v_max3_f32 v0, v0, v14, v15
	v_max_f32_e32 v14, v91, v91
	v_max_f32_e32 v15, v90, v90
	v_max_f32_e32 v14, v15, v14
	v_max_f32_e32 v15, v95, v95
	v_max_f32_e32 v112, v94, v94
	v_max_f32_e32 v15, v112, v15
	v_max3_f32 v14, v88, v89, v14
	v_max3_f32 v15, v92, v93, v15
	v_max3_f32 v0, v0, v14, v15
	v_mov_b32_e32 v14, v0
	s_nop 1
	v_permlane32_swap_b32_e32 v0, v14
	s_waitcnt lgkmcnt(0)
	v_max_f32_e32 v14, v14, v14
	v_max_f32_e32 v0, v0, v14
	v_cmp_gt_f32_e32 vcc, v0, v208
	s_cbranch_vccz .LBB0_711
	v_max_f32_e32 v0, v0, v0
	v_max_f32_e32 v14, v208, v208
	v_max_f32_e32 v14, v14, v0
	v_sub_f32_e32 v0, v208, v14
	v_exp_f32_e32 v0, v0
	v_mov_b32_e32 v208, v14
	v_mul_f32_e32 v209, v209, v0
	v_pk_mul_f32 v[78:79], v[78:79], v[0:1] op_sel_hi:[1,0]
	v_pk_mul_f32 v[76:77], v[76:77], v[0:1] op_sel_hi:[1,0]
	v_pk_mul_f32 v[74:75], v[74:75], v[0:1] op_sel_hi:[1,0]
	v_pk_mul_f32 v[72:73], v[72:73], v[0:1] op_sel_hi:[1,0]
	v_pk_mul_f32 v[70:71], v[70:71], v[0:1] op_sel_hi:[1,0]
	v_pk_mul_f32 v[68:69], v[68:69], v[0:1] op_sel_hi:[1,0]
	v_pk_mul_f32 v[66:67], v[66:67], v[0:1] op_sel_hi:[1,0]
	v_pk_mul_f32 v[64:65], v[64:65], v[0:1] op_sel_hi:[1,0]
	v_pk_mul_f32 v[62:63], v[62:63], v[0:1] op_sel_hi:[1,0]
	v_pk_mul_f32 v[60:61], v[60:61], v[0:1] op_sel_hi:[1,0]
	v_pk_mul_f32 v[58:59], v[58:59], v[0:1] op_sel_hi:[1,0]
	v_pk_mul_f32 v[56:57], v[56:57], v[0:1] op_sel_hi:[1,0]
	v_pk_mul_f32 v[54:55], v[54:55], v[0:1] op_sel_hi:[1,0]
	v_pk_mul_f32 v[52:53], v[52:53], v[0:1] op_sel_hi:[1,0]
	v_pk_mul_f32 v[50:51], v[50:51], v[0:1] op_sel_hi:[1,0]
	v_pk_mul_f32 v[48:49], v[48:49], v[0:1] op_sel_hi:[1,0]
	v_pk_mul_f32 v[46:47], v[46:47], v[0:1] op_sel_hi:[1,0]
	v_pk_mul_f32 v[44:45], v[44:45], v[0:1] op_sel_hi:[1,0]
	v_pk_mul_f32 v[42:43], v[42:43], v[0:1] op_sel_hi:[1,0]
	v_pk_mul_f32 v[40:41], v[40:41], v[0:1] op_sel_hi:[1,0]
	v_pk_mul_f32 v[38:39], v[38:39], v[0:1] op_sel_hi:[1,0]
	v_pk_mul_f32 v[36:37], v[36:37], v[0:1] op_sel_hi:[1,0]
	v_pk_mul_f32 v[34:35], v[34:35], v[0:1] op_sel_hi:[1,0]
	v_pk_mul_f32 v[32:33], v[32:33], v[0:1] op_sel_hi:[1,0]
	v_pk_mul_f32 v[30:31], v[30:31], v[0:1] op_sel_hi:[1,0]
	v_pk_mul_f32 v[28:29], v[28:29], v[0:1] op_sel_hi:[1,0]
	v_pk_mul_f32 v[26:27], v[26:27], v[0:1] op_sel_hi:[1,0]
	v_pk_mul_f32 v[24:25], v[24:25], v[0:1] op_sel_hi:[1,0]
	v_pk_mul_f32 v[22:23], v[22:23], v[0:1] op_sel_hi:[1,0]
	v_pk_mul_f32 v[20:21], v[20:21], v[0:1] op_sel_hi:[1,0]
	v_pk_mul_f32 v[18:19], v[18:19], v[0:1] op_sel_hi:[1,0]
	v_pk_mul_f32 v[16:17], v[16:17], v[0:1] op_sel_hi:[1,0]

.LBB0_713:
	s_waitcnt vmcnt(3)
	v_mfma_f32_32x32x16_bf16 v[80:95], v[112:115], v[108:111], 0
	v_lshl_add_u64 v[14:15], s[26:27], 0, v[150:151]
	v_add_co_u32_e32 v112, vcc, 0xe510000, v14
	s_nop 1
	v_addc_co_u32_e32 v113, vcc, 0, v15, vcc
	global_load_dwordx4 v[144:147], v[112:113], off
	global_load_dwordx4 v[128:131], v[112:113], off offset:1024
	s_waitcnt vmcnt(4)
	v_mfma_f32_32x32x16_bf16 v[80:95], v[10:13], v[104:107], v[80:95]
	v_add_co_u32_e32 v10, vcc, 0xe511000, v14
	global_load_dwordx4 v[136:139], v[112:113], off offset:2048
	global_load_dwordx4 v[140:143], v[112:113], off offset:3072
	v_addc_co_u32_e32 v11, vcc, 0, v15, vcc
	global_load_dwordx4 v[132:135], v[10:11], off
	global_load_dwordx4 v[124:127], v[10:11], off offset:1024
	global_load_dwordx4 v[116:119], v[10:11], off offset:2048
	global_load_dwordx4 v[120:123], v[10:11], off offset:3072
	v_lshl_add_u64 v[14:15], s[24:25], 0, v[150:151]
	s_waitcnt vmcnt(9)
	v_mfma_f32_32x32x16_bf16 v[80:95], v[6:9], v[100:103], v[80:95]
	global_load_dwordx4 v[112:115], v[14:15], off offset:-2048
	global_load_dwordx4 v[10:13], v[14:15], off offset:-1024
	s_waitcnt vmcnt(10)
	v_mfma_f32_32x32x16_bf16 v[80:95], v[2:5], v[96:99], v[80:95]
	global_load_dwordx4 v[6:9], v[14:15], off
	global_load_dwordx4 v[2:5], v[14:15], off offset:1024
	s_nop 9
	v_max_f32_e32 v14, v81, v81
	v_max_f32_e32 v15, v80, v80
	v_max_f32_e32 v14, v15, v14
	v_max_f32_e32 v15, v83, v83
	v_max_f32_e32 v209, v82, v82
	v_max_f32_e32 v15, v209, v15
	v_max_f32_e32 v209, v87, v87
	v_max_f32_e32 v212, v86, v86
	v_max_f32_e32 v209, v212, v209
	v_max3_f32 v209, v84, v85, v209
	v_max3_f32 v14, v14, v15, v209
	v_max_f32_e32 v15, v91, v91
	v_max_f32_e32 v209, v90, v90
	v_max_f32_e32 v15, v209, v15
	v_max_f32_e32 v209, v95, v95
	v_max_f32_e32 v212, v94, v94
	v_max_f32_e32 v209, v212, v209
	v_max3_f32 v15, v88, v89, v15
	v_max3_f32 v209, v92, v93, v209
	v_max3_f32 v14, v14, v15, v209
	v_mov_b32_e32 v15, v14
	s_nop 1
	v_permlane32_swap_b32_e32 v14, v15
	s_waitcnt lgkmcnt(0)
	v_max_f32_e32 v15, v15, v15
	v_max_f32_e32 v14, v14, v15
	v_cmp_gt_f32_e32 vcc, v14, v208
	s_cbranch_vccz .LBB0_712
	v_max_f32_e32 v14, v14, v14
	v_max_f32_e32 v15, v208, v208
	v_max_f32_e32 v15, v15, v14
	v_sub_f32_e32 v14, v208, v15
	v_exp_f32_e32 v14, v14
	v_mov_b32_e32 v208, v15
	v_mul_f32_e32 v0, v0, v14
	v_pk_mul_f32 v[78:79], v[78:79], v[14:15] op_sel_hi:[1,0]
	v_pk_mul_f32 v[76:77], v[76:77], v[14:15] op_sel_hi:[1,0]
	v_pk_mul_f32 v[74:75], v[74:75], v[14:15] op_sel_hi:[1,0]
	v_pk_mul_f32 v[72:73], v[72:73], v[14:15] op_sel_hi:[1,0]
	v_pk_mul_f32 v[70:71], v[70:71], v[14:15] op_sel_hi:[1,0]
	v_pk_mul_f32 v[68:69], v[68:69], v[14:15] op_sel_hi:[1,0]
	v_pk_mul_f32 v[66:67], v[66:67], v[14:15] op_sel_hi:[1,0]
	v_pk_mul_f32 v[64:65], v[64:65], v[14:15] op_sel_hi:[1,0]
	v_pk_mul_f32 v[62:63], v[62:63], v[14:15] op_sel_hi:[1,0]
	v_pk_mul_f32 v[60:61], v[60:61], v[14:15] op_sel_hi:[1,0]
	v_pk_mul_f32 v[58:59], v[58:59], v[14:15] op_sel_hi:[1,0]
	v_pk_mul_f32 v[56:57], v[56:57], v[14:15] op_sel_hi:[1,0]
	v_pk_mul_f32 v[54:55], v[54:55], v[14:15] op_sel_hi:[1,0]
	v_pk_mul_f32 v[52:53], v[52:53], v[14:15] op_sel_hi:[1,0]
	v_pk_mul_f32 v[50:51], v[50:51], v[14:15] op_sel_hi:[1,0]
	v_pk_mul_f32 v[48:49], v[48:49], v[14:15] op_sel_hi:[1,0]
	v_pk_mul_f32 v[46:47], v[46:47], v[14:15] op_sel_hi:[1,0]
	v_pk_mul_f32 v[44:45], v[44:45], v[14:15] op_sel_hi:[1,0]
	v_pk_mul_f32 v[42:43], v[42:43], v[14:15] op_sel_hi:[1,0]
	v_pk_mul_f32 v[40:41], v[40:41], v[14:15] op_sel_hi:[1,0]
	v_pk_mul_f32 v[38:39], v[38:39], v[14:15] op_sel_hi:[1,0]
	v_pk_mul_f32 v[36:37], v[36:37], v[14:15] op_sel_hi:[1,0]
	v_pk_mul_f32 v[34:35], v[34:35], v[14:15] op_sel_hi:[1,0]
	v_pk_mul_f32 v[32:33], v[32:33], v[14:15] op_sel_hi:[1,0]
	v_pk_mul_f32 v[30:31], v[30:31], v[14:15] op_sel_hi:[1,0]
	v_pk_mul_f32 v[28:29], v[28:29], v[14:15] op_sel_hi:[1,0]
	v_pk_mul_f32 v[26:27], v[26:27], v[14:15] op_sel_hi:[1,0]
	v_pk_mul_f32 v[24:25], v[24:25], v[14:15] op_sel_hi:[1,0]
	v_pk_mul_f32 v[22:23], v[22:23], v[14:15] op_sel_hi:[1,0]
	v_pk_mul_f32 v[20:21], v[20:21], v[14:15] op_sel_hi:[1,0]
	v_pk_mul_f32 v[18:19], v[18:19], v[14:15] op_sel_hi:[1,0]
	v_pk_mul_f32 v[16:17], v[16:17], v[14:15] op_sel_hi:[1,0]
	s_branch .LBB0_712
.LBB0_715:
	s_waitcnt vmcnt(3)
	v_mfma_f32_32x32x16_bf16 v[80:95], v[112:115], v[108:111], 0
	s_waitcnt vmcnt(2)
	v_mfma_f32_32x32x16_bf16 v[80:95], v[10:13], v[104:107], v[80:95]
	global_load_dwordx4 v[124:127], v[172:173], off
	global_load_dwordx4 v[120:123], v[174:175], off
	global_load_dwordx4 v[116:119], v[176:177], off
	global_load_dwordx4 v[112:115], v[178:179], off
	global_load_dwordx4 v[108:111], v[180:181], off
	global_load_dwordx4 v[104:107], v[182:183], off
	s_waitcnt vmcnt(7)
	v_mfma_f32_32x32x16_bf16 v[80:95], v[6:9], v[100:103], v[80:95]
	global_load_dwordx4 v[10:13], v[184:185], off
	global_load_dwordx4 v[6:9], v[186:187], off
	s_waitcnt vmcnt(8)
	v_mfma_f32_32x32x16_bf16 v[80:95], v[2:5], v[96:99], v[80:95]
	s_nop 11
	v_max_f32_e32 v2, v81, v81
	v_max_f32_e32 v3, v80, v80
	v_max_f32_e32 v2, v3, v2
	v_max_f32_e32 v3, v83, v83
	v_max_f32_e32 v4, v82, v82
	v_max_f32_e32 v3, v4, v3
	v_max_f32_e32 v4, v87, v87
	v_max_f32_e32 v5, v86, v86
	v_max_f32_e32 v4, v5, v4
	v_max3_f32 v4, v84, v85, v4
	v_max3_f32 v2, v2, v3, v4
	v_max_f32_e32 v3, v91, v91
	v_max_f32_e32 v4, v90, v90
	v_max_f32_e32 v3, v4, v3
	v_max_f32_e32 v4, v95, v95
	v_max_f32_e32 v5, v94, v94
	v_max_f32_e32 v4, v5, v4
	v_max3_f32 v3, v88, v89, v3
	v_max3_f32 v4, v92, v93, v4
	v_max3_f32 v2, v2, v3, v4
	v_mov_b32_e32 v3, v2
	s_nop 1
	v_permlane32_swap_b32_e32 v2, v3
	s_waitcnt lgkmcnt(0)
	v_max_f32_e32 v3, v3, v3
	v_max_f32_e32 v2, v2, v3
	v_cmp_gt_f32_e32 vcc, v2, v208
	s_cbranch_vccz .LBB0_717
	v_max_f32_e32 v2, v2, v2
	v_max_f32_e32 v3, v208, v208
	v_max_f32_e32 v3, v3, v2
	v_sub_f32_e32 v2, v208, v3
	v_exp_f32_e32 v2, v2
	v_mov_b32_e32 v208, v3
	v_mul_f32_e32 v0, v0, v2
	v_pk_mul_f32 v[78:79], v[78:79], v[2:3] op_sel_hi:[1,0]
	v_pk_mul_f32 v[76:77], v[76:77], v[2:3] op_sel_hi:[1,0]
	v_pk_mul_f32 v[74:75], v[74:75], v[2:3] op_sel_hi:[1,0]
	v_pk_mul_f32 v[72:73], v[72:73], v[2:3] op_sel_hi:[1,0]
	v_pk_mul_f32 v[70:71], v[70:71], v[2:3] op_sel_hi:[1,0]
	v_pk_mul_f32 v[68:69], v[68:69], v[2:3] op_sel_hi:[1,0]
	v_pk_mul_f32 v[66:67], v[66:67], v[2:3] op_sel_hi:[1,0]
	v_pk_mul_f32 v[64:65], v[64:65], v[2:3] op_sel_hi:[1,0]
	v_pk_mul_f32 v[62:63], v[62:63], v[2:3] op_sel_hi:[1,0]
	v_pk_mul_f32 v[60:61], v[60:61], v[2:3] op_sel_hi:[1,0]
	v_pk_mul_f32 v[58:59], v[58:59], v[2:3] op_sel_hi:[1,0]
	v_pk_mul_f32 v[56:57], v[56:57], v[2:3] op_sel_hi:[1,0]
	v_pk_mul_f32 v[54:55], v[54:55], v[2:3] op_sel_hi:[1,0]
	v_pk_mul_f32 v[52:53], v[52:53], v[2:3] op_sel_hi:[1,0]
	v_pk_mul_f32 v[50:51], v[50:51], v[2:3] op_sel_hi:[1,0]
	v_pk_mul_f32 v[48:49], v[48:49], v[2:3] op_sel_hi:[1,0]
	v_pk_mul_f32 v[46:47], v[46:47], v[2:3] op_sel_hi:[1,0]
	v_pk_mul_f32 v[44:45], v[44:45], v[2:3] op_sel_hi:[1,0]
	v_pk_mul_f32 v[42:43], v[42:43], v[2:3] op_sel_hi:[1,0]
	v_pk_mul_f32 v[40:41], v[40:41], v[2:3] op_sel_hi:[1,0]
	v_pk_mul_f32 v[38:39], v[38:39], v[2:3] op_sel_hi:[1,0]
	v_pk_mul_f32 v[36:37], v[36:37], v[2:3] op_sel_hi:[1,0]
	v_pk_mul_f32 v[34:35], v[34:35], v[2:3] op_sel_hi:[1,0]
	v_pk_mul_f32 v[32:33], v[32:33], v[2:3] op_sel_hi:[1,0]
	v_pk_mul_f32 v[30:31], v[30:31], v[2:3] op_sel_hi:[1,0]
	v_pk_mul_f32 v[28:29], v[28:29], v[2:3] op_sel_hi:[1,0]
	v_pk_mul_f32 v[26:27], v[26:27], v[2:3] op_sel_hi:[1,0]
	v_pk_mul_f32 v[24:25], v[24:25], v[2:3] op_sel_hi:[1,0]
	v_pk_mul_f32 v[22:23], v[22:23], v[2:3] op_sel_hi:[1,0]
	v_pk_mul_f32 v[20:21], v[20:21], v[2:3] op_sel_hi:[1,0]
	v_pk_mul_f32 v[18:19], v[18:19], v[2:3] op_sel_hi:[1,0]
	v_pk_mul_f32 v[16:17], v[16:17], v[2:3] op_sel_hi:[1,0]

.LBB0_736:
	s_waitcnt vmcnt(3)
	v_mfma_f32_32x32x16_bf16 v[80:95], v[124:127], v[108:111], 0
	v_lshl_add_u64 v[2:3], s[26:27], 0, v[150:151]
	v_add_co_u32_e32 v4, vcc, 0xc500000, v2
	v_lshl_add_u64 v[14:15], s[24:25], 0, v[150:151]
	s_nop 0
	v_addc_co_u32_e32 v5, vcc, 0, v3, vcc
	v_add_co_u32_e32 v6, vcc, 0xc501000, v2
	s_waitcnt vmcnt(2)
	v_mfma_f32_32x32x16_bf16 v[80:95], v[120:123], v[104:107], v[80:95]
	v_addc_co_u32_e32 v7, vcc, 0, v3, vcc
	global_load_dwordx4 v[144:147], v[4:5], off
	global_load_dwordx4 v[128:131], v[4:5], off offset:1024
	global_load_dwordx4 v[136:139], v[4:5], off offset:2048
	global_load_dwordx4 v[140:143], v[4:5], off offset:3072
	global_load_dwordx4 v[132:135], v[6:7], off
	global_load_dwordx4 v[10:13], v[6:7], off offset:1024
	s_nop 0
	global_load_dwordx4 v[2:5], v[6:7], off offset:2048
	s_nop 0
	global_load_dwordx4 v[6:9], v[6:7], off offset:3072
	s_nop 0
	global_load_dwordx4 v[124:127], v[14:15], off offset:-2048
	global_load_dwordx4 v[120:123], v[14:15], off offset:-1024
	s_waitcnt vmcnt(11)
	v_mfma_f32_32x32x16_bf16 v[80:95], v[116:119], v[100:103], v[80:95]
	s_waitcnt vmcnt(10)
	v_mfma_f32_32x32x16_bf16 v[80:95], v[112:115], v[96:99], v[80:95]
	global_load_dwordx4 v[116:119], v[14:15], off
	global_load_dwordx4 v[112:115], v[14:15], off offset:1024
	s_nop 9
	v_max_f32_e32 v0, v81, v81
	v_max_f32_e32 v14, v80, v80
	v_max_f32_e32 v0, v14, v0
	v_max_f32_e32 v14, v83, v83
	v_max_f32_e32 v15, v82, v82
	v_max_f32_e32 v14, v15, v14
	v_max_f32_e32 v15, v87, v87
	v_max_f32_e32 v189, v86, v86
	v_max_f32_e32 v15, v189, v15
	v_max3_f32 v15, v84, v85, v15
	v_max3_f32 v0, v0, v14, v15
	v_max_f32_e32 v14, v91, v91
	v_max_f32_e32 v15, v90, v90
	v_max_f32_e32 v14, v15, v14
	v_max_f32_e32 v15, v95, v95
	v_max_f32_e32 v189, v94, v94
	v_max_f32_e32 v15, v189, v15
	v_max3_f32 v14, v88, v89, v14
	v_max3_f32 v15, v92, v93, v15
	v_max3_f32 v0, v0, v14, v15
	v_mov_b32_e32 v14, v0
	s_nop 1
	v_permlane32_swap_b32_e32 v0, v14
	s_waitcnt lgkmcnt(0)
	v_max_f32_e32 v14, v14, v14
	v_max_f32_e32 v0, v0, v14
	v_cmp_gt_f32_e32 vcc, v0, v188
	s_cbranch_vccz .LBB0_735
	v_max_f32_e32 v0, v0, v0
	v_max_f32_e32 v14, v188, v188
	v_max_f32_e32 v14, v14, v0
	v_sub_f32_e32 v0, v188, v14
	v_exp_f32_e32 v0, v0
	v_mov_b32_e32 v188, v14
	v_mul_f32_e32 v187, v187, v0
	v_pk_mul_f32 v[78:79], v[78:79], v[0:1] op_sel_hi:[1,0]
	v_pk_mul_f32 v[76:77], v[76:77], v[0:1] op_sel_hi:[1,0]
	v_pk_mul_f32 v[74:75], v[74:75], v[0:1] op_sel_hi:[1,0]
	v_pk_mul_f32 v[72:73], v[72:73], v[0:1] op_sel_hi:[1,0]
	v_pk_mul_f32 v[70:71], v[70:71], v[0:1] op_sel_hi:[1,0]
	v_pk_mul_f32 v[68:69], v[68:69], v[0:1] op_sel_hi:[1,0]
	v_pk_mul_f32 v[66:67], v[66:67], v[0:1] op_sel_hi:[1,0]
	v_pk_mul_f32 v[64:65], v[64:65], v[0:1] op_sel_hi:[1,0]
	v_pk_mul_f32 v[62:63], v[62:63], v[0:1] op_sel_hi:[1,0]
	v_pk_mul_f32 v[60:61], v[60:61], v[0:1] op_sel_hi:[1,0]
	v_pk_mul_f32 v[58:59], v[58:59], v[0:1] op_sel_hi:[1,0]
	v_pk_mul_f32 v[56:57], v[56:57], v[0:1] op_sel_hi:[1,0]
	v_pk_mul_f32 v[54:55], v[54:55], v[0:1] op_sel_hi:[1,0]
	v_pk_mul_f32 v[52:53], v[52:53], v[0:1] op_sel_hi:[1,0]
	v_pk_mul_f32 v[50:51], v[50:51], v[0:1] op_sel_hi:[1,0]
	v_pk_mul_f32 v[48:49], v[48:49], v[0:1] op_sel_hi:[1,0]
	v_pk_mul_f32 v[46:47], v[46:47], v[0:1] op_sel_hi:[1,0]
	v_pk_mul_f32 v[44:45], v[44:45], v[0:1] op_sel_hi:[1,0]
	v_pk_mul_f32 v[42:43], v[42:43], v[0:1] op_sel_hi:[1,0]
	v_pk_mul_f32 v[40:41], v[40:41], v[0:1] op_sel_hi:[1,0]
	v_pk_mul_f32 v[38:39], v[38:39], v[0:1] op_sel_hi:[1,0]
	v_pk_mul_f32 v[36:37], v[36:37], v[0:1] op_sel_hi:[1,0]
	v_pk_mul_f32 v[34:35], v[34:35], v[0:1] op_sel_hi:[1,0]
	v_pk_mul_f32 v[32:33], v[32:33], v[0:1] op_sel_hi:[1,0]
	v_pk_mul_f32 v[30:31], v[30:31], v[0:1] op_sel_hi:[1,0]
	v_pk_mul_f32 v[28:29], v[28:29], v[0:1] op_sel_hi:[1,0]
	v_pk_mul_f32 v[26:27], v[26:27], v[0:1] op_sel_hi:[1,0]
	v_pk_mul_f32 v[24:25], v[24:25], v[0:1] op_sel_hi:[1,0]
	v_pk_mul_f32 v[22:23], v[22:23], v[0:1] op_sel_hi:[1,0]
	v_pk_mul_f32 v[20:21], v[20:21], v[0:1] op_sel_hi:[1,0]
	v_pk_mul_f32 v[18:19], v[18:19], v[0:1] op_sel_hi:[1,0]
	v_pk_mul_f32 v[16:17], v[16:17], v[0:1] op_sel_hi:[1,0]
	s_branch .LBB0_735
.LBB0_738:
	s_waitcnt vmcnt(3)
	v_mfma_f32_32x32x16_bf16 v[80:95], v[124:127], v[108:111], 0
	s_waitcnt vmcnt(2)
	v_mfma_f32_32x32x16_bf16 v[80:95], v[120:123], v[104:107], v[80:95]
	global_load_dwordx4 v[128:131], v[154:155], off
	global_load_dwordx4 v[124:127], v[156:157], off
	global_load_dwordx4 v[120:123], v[158:159], off
	global_load_dwordx4 v[108:111], v[160:161], off
	global_load_dwordx4 v[104:107], v[162:163], off
	global_load_dwordx4 v[10:13], v[164:165], off
	global_load_dwordx4 v[6:9], v[166:167], off
	global_load_dwordx4 v[2:5], v[168:169], off
	s_waitcnt vmcnt(9)
	v_mfma_f32_32x32x16_bf16 v[80:95], v[116:119], v[100:103], v[80:95]
	s_waitcnt vmcnt(8)
	v_mfma_f32_32x32x16_bf16 v[80:95], v[112:115], v[96:99], v[80:95]
	s_nop 11
	v_max_f32_e32 v0, v81, v81
	v_max_f32_e32 v14, v80, v80
	v_max_f32_e32 v0, v14, v0
	v_max_f32_e32 v14, v83, v83
	v_max_f32_e32 v15, v82, v82
	v_max_f32_e32 v14, v15, v14
	v_max_f32_e32 v15, v87, v87
	v_max_f32_e32 v96, v86, v86
	v_max_f32_e32 v15, v96, v15
	v_max3_f32 v15, v84, v85, v15
	v_max3_f32 v0, v0, v14, v15
	v_max_f32_e32 v14, v91, v91
	v_max_f32_e32 v15, v90, v90
	v_max_f32_e32 v14, v15, v14
	v_max_f32_e32 v15, v95, v95
	v_max_f32_e32 v96, v94, v94
	v_max_f32_e32 v15, v96, v15
	v_max3_f32 v14, v88, v89, v14
	v_max3_f32 v15, v92, v93, v15
	v_max3_f32 v0, v0, v14, v15
	v_mov_b32_e32 v14, v0
	s_nop 1
	v_permlane32_swap_b32_e32 v0, v14
	s_waitcnt lgkmcnt(0)
	v_max_f32_e32 v14, v14, v14
	v_max_f32_e32 v0, v0, v14
	v_cmp_gt_f32_e32 vcc, v0, v188
	s_cbranch_vccz .LBB0_740
	v_max_f32_e32 v0, v0, v0
	v_max_f32_e32 v14, v188, v188
	v_max_f32_e32 v14, v14, v0
	v_sub_f32_e32 v0, v188, v14
	v_exp_f32_e32 v0, v0
	v_mov_b32_e32 v188, v14
	v_mul_f32_e32 v187, v187, v0
	v_pk_mul_f32 v[78:79], v[78:79], v[0:1] op_sel_hi:[1,0]
	v_pk_mul_f32 v[76:77], v[76:77], v[0:1] op_sel_hi:[1,0]
	v_pk_mul_f32 v[74:75], v[74:75], v[0:1] op_sel_hi:[1,0]
	v_pk_mul_f32 v[72:73], v[72:73], v[0:1] op_sel_hi:[1,0]
	v_pk_mul_f32 v[70:71], v[70:71], v[0:1] op_sel_hi:[1,0]
	v_pk_mul_f32 v[68:69], v[68:69], v[0:1] op_sel_hi:[1,0]
	v_pk_mul_f32 v[66:67], v[66:67], v[0:1] op_sel_hi:[1,0]
	v_pk_mul_f32 v[64:65], v[64:65], v[0:1] op_sel_hi:[1,0]
	v_pk_mul_f32 v[62:63], v[62:63], v[0:1] op_sel_hi:[1,0]
	v_pk_mul_f32 v[60:61], v[60:61], v[0:1] op_sel_hi:[1,0]
	v_pk_mul_f32 v[58:59], v[58:59], v[0:1] op_sel_hi:[1,0]
	v_pk_mul_f32 v[56:57], v[56:57], v[0:1] op_sel_hi:[1,0]
	v_pk_mul_f32 v[54:55], v[54:55], v[0:1] op_sel_hi:[1,0]
	v_pk_mul_f32 v[52:53], v[52:53], v[0:1] op_sel_hi:[1,0]
	v_pk_mul_f32 v[50:51], v[50:51], v[0:1] op_sel_hi:[1,0]
	v_pk_mul_f32 v[48:49], v[48:49], v[0:1] op_sel_hi:[1,0]
	v_pk_mul_f32 v[46:47], v[46:47], v[0:1] op_sel_hi:[1,0]
	v_pk_mul_f32 v[44:45], v[44:45], v[0:1] op_sel_hi:[1,0]
	v_pk_mul_f32 v[42:43], v[42:43], v[0:1] op_sel_hi:[1,0]
	v_pk_mul_f32 v[40:41], v[40:41], v[0:1] op_sel_hi:[1,0]
	v_pk_mul_f32 v[38:39], v[38:39], v[0:1] op_sel_hi:[1,0]
	v_pk_mul_f32 v[36:37], v[36:37], v[0:1] op_sel_hi:[1,0]
	v_pk_mul_f32 v[34:35], v[34:35], v[0:1] op_sel_hi:[1,0]
	v_pk_mul_f32 v[32:33], v[32:33], v[0:1] op_sel_hi:[1,0]
	v_pk_mul_f32 v[30:31], v[30:31], v[0:1] op_sel_hi:[1,0]
	v_pk_mul_f32 v[28:29], v[28:29], v[0:1] op_sel_hi:[1,0]
	v_pk_mul_f32 v[26:27], v[26:27], v[0:1] op_sel_hi:[1,0]
	v_pk_mul_f32 v[24:25], v[24:25], v[0:1] op_sel_hi:[1,0]
	v_pk_mul_f32 v[22:23], v[22:23], v[0:1] op_sel_hi:[1,0]
	v_pk_mul_f32 v[20:21], v[20:21], v[0:1] op_sel_hi:[1,0]
	v_pk_mul_f32 v[18:19], v[18:19], v[0:1] op_sel_hi:[1,0]
	v_pk_mul_f32 v[16:17], v[16:17], v[0:1] op_sel_hi:[1,0]
